# pool/gmlp/fourier_out output stores widened: 16 dwordx2 -> 8 dwordx4 per 16-row tile via v_permlane16_swap (64 contiguous bytes per row)
# speedup vs baseline: 1.0028x; 1.0026x over previous
.LBB0_235:
	global_load_dwordx4 v[90:93], v[74:75], off
	global_load_dwordx4 v[94:97], v[72:73], off
	global_load_dwordx4 v[106:109], v[72:73], off offset:2048
	global_load_dwordx4 v[110:113], v[76:77], off
	v_add_u32_e32 v56, s9, v137
	v_mov_b32_e32 v131, v209
	s_ashr_i32 s11, s9, 31
	s_lshr_b32 s11, s11, 19
	s_add_i32 s11, s9, s11
	s_and_b32 s11, s11, 0xffffe000
	s_sub_i32 s11, s9, s11
	s_add_i32 s18, s11, -8
	s_add_i32 s0, s0, s3
	s_add_u32 s100, s84, s58
	s_addc_u32 s101, s85, 0
	v_add_u32_e32 v0, 0, v56
	v_max_i32_e32 v0, 8, v0
	v_add_u32_e32 v0, -8, v0
	v_min_u32_e32 v0, 0xffff, v0
	v_mul_u32_u24_e32 v208, 0xe00, v0
	v_lshl_add_u64 v[0:1], s[100:101], 0, v[208:209]
	v_lshl_add_u64 v[0:1], v[0:1], 0, v[130:131]
	global_load_dwordx4 v[0:3], v[0:1], off offset:1536
	v_add_u32_e32 v4, 2, v56
	v_max_i32_e32 v4, 8, v4
	v_add_u32_e32 v4, -8, v4
	v_min_u32_e32 v4, 0xffff, v4
	v_mul_u32_u24_e32 v208, 0xe00, v4
	v_lshl_add_u64 v[4:5], s[100:101], 0, v[208:209]
	v_lshl_add_u64 v[4:5], v[4:5], 0, v[130:131]
	global_load_dwordx4 v[4:7], v[4:5], off offset:1536
	v_add_u32_e32 v8, 4, v56
	v_max_i32_e32 v8, 8, v8
	v_add_u32_e32 v8, -8, v8
	v_min_u32_e32 v8, 0xffff, v8
	v_mul_u32_u24_e32 v208, 0xe00, v8
	v_lshl_add_u64 v[8:9], s[100:101], 0, v[208:209]
	v_lshl_add_u64 v[8:9], v[8:9], 0, v[130:131]
	global_load_dwordx4 v[8:11], v[8:9], off offset:1536
	v_add_u32_e32 v12, 6, v56
	v_max_i32_e32 v12, 8, v12
	v_add_u32_e32 v12, -8, v12
	v_min_u32_e32 v12, 0xffff, v12
	v_mul_u32_u24_e32 v208, 0xe00, v12
	v_lshl_add_u64 v[12:13], s[100:101], 0, v[208:209]
	v_lshl_add_u64 v[12:13], v[12:13], 0, v[130:131]
	global_load_dwordx4 v[12:15], v[12:13], off offset:1536
	v_add_u32_e32 v16, 8, v56
	v_max_i32_e32 v16, 8, v16
	v_add_u32_e32 v16, -8, v16
	v_min_u32_e32 v16, 0xffff, v16
	v_mul_u32_u24_e32 v208, 0xe00, v16
	v_lshl_add_u64 v[16:17], s[100:101], 0, v[208:209]
	v_lshl_add_u64 v[16:17], v[16:17], 0, v[130:131]
	global_load_dwordx4 v[16:19], v[16:17], off offset:1536
	v_add_u32_e32 v20, 10, v56
	v_max_i32_e32 v20, 8, v20
	v_add_u32_e32 v20, -8, v20
	v_min_u32_e32 v20, 0xffff, v20
	v_mul_u32_u24_e32 v208, 0xe00, v20
	v_lshl_add_u64 v[20:21], s[100:101], 0, v[208:209]
	v_lshl_add_u64 v[20:21], v[20:21], 0, v[130:131]
	global_load_dwordx4 v[20:23], v[20:21], off offset:1536
	v_add_u32_e32 v24, 12, v56
	v_max_i32_e32 v24, 8, v24
	v_add_u32_e32 v24, -8, v24
	v_min_u32_e32 v24, 0xffff, v24
	v_mul_u32_u24_e32 v208, 0xe00, v24
	v_lshl_add_u64 v[24:25], s[100:101], 0, v[208:209]
	v_lshl_add_u64 v[24:25], v[24:25], 0, v[130:131]
	global_load_dwordx4 v[24:27], v[24:25], off offset:1536
	v_add_u32_e32 v28, 14, v56
	v_max_i32_e32 v28, 8, v28
	v_add_u32_e32 v28, -8, v28
	v_min_u32_e32 v28, 0xffff, v28
	v_mul_u32_u24_e32 v208, 0xe00, v28
	v_lshl_add_u64 v[28:29], s[100:101], 0, v[208:209]
	v_lshl_add_u64 v[28:29], v[28:29], 0, v[130:131]
	global_load_dwordx4 v[28:31], v[28:29], off offset:1536
	v_add_u32_e32 v32, 16, v56
	v_max_i32_e32 v32, 8, v32
	v_add_u32_e32 v32, -8, v32
	v_min_u32_e32 v32, 0xffff, v32
	v_mul_u32_u24_e32 v208, 0xe00, v32
	v_lshl_add_u64 v[32:33], s[100:101], 0, v[208:209]
	v_lshl_add_u64 v[32:33], v[32:33], 0, v[130:131]
	global_load_dwordx4 v[32:35], v[32:33], off offset:1536
	v_add_u32_e32 v36, 18, v56
	v_max_i32_e32 v36, 8, v36
	v_add_u32_e32 v36, -8, v36
	v_min_u32_e32 v36, 0xffff, v36
	v_mul_u32_u24_e32 v208, 0xe00, v36
	v_lshl_add_u64 v[36:37], s[100:101], 0, v[208:209]
	v_lshl_add_u64 v[36:37], v[36:37], 0, v[130:131]
	global_load_dwordx4 v[36:39], v[36:37], off offset:1536
	v_add_u32_e32 v40, 20, v56
	v_max_i32_e32 v40, 8, v40
	v_add_u32_e32 v40, -8, v40
	v_min_u32_e32 v40, 0xffff, v40
	v_mul_u32_u24_e32 v208, 0xe00, v40
	v_lshl_add_u64 v[40:41], s[100:101], 0, v[208:209]
	v_lshl_add_u64 v[40:41], v[40:41], 0, v[130:131]
	global_load_dwordx4 v[40:43], v[40:41], off offset:1536
	v_add_u32_e32 v44, 22, v56
	v_max_i32_e32 v44, 8, v44
	v_add_u32_e32 v44, -8, v44
	v_min_u32_e32 v44, 0xffff, v44
	v_mul_u32_u24_e32 v208, 0xe00, v44
	v_lshl_add_u64 v[44:45], s[100:101], 0, v[208:209]
	v_lshl_add_u64 v[44:45], v[44:45], 0, v[130:131]
	global_load_dwordx4 v[44:47], v[44:45], off offset:1536
	v_add_u32_e32 v48, 24, v56
	v_max_i32_e32 v48, 8, v48
	v_add_u32_e32 v48, -8, v48
	v_min_u32_e32 v48, 0xffff, v48
	v_mul_u32_u24_e32 v208, 0xe00, v48
	v_lshl_add_u64 v[48:49], s[100:101], 0, v[208:209]
	v_lshl_add_u64 v[48:49], v[48:49], 0, v[130:131]
	global_load_dwordx4 v[48:51], v[48:49], off offset:1536
	v_add_u32_e32 v52, 26, v56
	v_max_i32_e32 v52, 8, v52
	v_add_u32_e32 v52, -8, v52
	v_min_u32_e32 v52, 0xffff, v52
	v_mul_u32_u24_e32 v208, 0xe00, v52
	v_lshl_add_u64 v[52:53], s[100:101], 0, v[208:209]
	v_lshl_add_u64 v[52:53], v[52:53], 0, v[130:131]
	global_load_dwordx4 v[52:55], v[52:53], off offset:1536
	v_add_u32_e32 v58, 28, v56
	v_max_i32_e32 v58, 8, v58
	v_add_u32_e32 v58, -8, v58
	v_min_u32_e32 v58, 0xffff, v58
	v_mul_u32_u24_e32 v208, 0xe00, v58
	v_lshl_add_u64 v[58:59], s[100:101], 0, v[208:209]
	v_lshl_add_u64 v[58:59], v[58:59], 0, v[130:131]
	global_load_dwordx4 v[58:61], v[58:59], off offset:1536
	v_add_u32_e32 v62, 30, v56
	v_max_i32_e32 v62, 8, v62
	v_add_u32_e32 v62, -8, v62
	v_min_u32_e32 v62, 0xffff, v62
	v_mul_u32_u24_e32 v208, 0xe00, v62
	v_lshl_add_u64 v[62:63], s[100:101], 0, v[208:209]
	v_lshl_add_u64 v[62:63], v[62:63], 0, v[130:131]
	global_load_dwordx4 v[62:65], v[62:63], off offset:1536
	s_cmpk_lt_u32 s18, 0x2000
	s_cselect_b64 vcc, -1, 0
	s_waitcnt vmcnt(15)
	v_cndmask_b32_e32 v3, 0, v3, vcc
	v_cndmask_b32_e32 v2, 0, v2, vcc
	v_cndmask_b32_e32 v1, 0, v1, vcc
	v_cndmask_b32_e32 v0, 0, v0, vcc
	s_waitcnt vmcnt(14)
	v_cndmask_b32_e32 v7, 0, v7, vcc
	v_cndmask_b32_e32 v6, 0, v6, vcc
	v_cndmask_b32_e32 v5, 0, v5, vcc
	v_cndmask_b32_e32 v4, 0, v4, vcc
	s_waitcnt vmcnt(13)
	v_cndmask_b32_e32 v11, 0, v11, vcc
	v_cndmask_b32_e32 v10, 0, v10, vcc
	v_cndmask_b32_e32 v9, 0, v9, vcc
	v_cndmask_b32_e32 v8, 0, v8, vcc
	s_waitcnt vmcnt(12)
	v_cndmask_b32_e32 v15, 0, v15, vcc
	v_cndmask_b32_e32 v14, 0, v14, vcc
	v_cndmask_b32_e32 v13, 0, v13, vcc
	v_cndmask_b32_e32 v12, 0, v12, vcc
	s_cmp_gt_i32 s11, -1
	s_cselect_b64 vcc, -1, 0
	s_waitcnt vmcnt(11)
	v_cndmask_b32_e32 v19, 0, v19, vcc
	v_cndmask_b32_e32 v18, 0, v18, vcc
	v_cndmask_b32_e32 v17, 0, v17, vcc
	v_cndmask_b32_e32 v16, 0, v16, vcc
	v_add_u32_e32 v206, s18, v138
	v_cmp_gt_u32_e32 vcc, s15, v206
	s_waitcnt vmcnt(10)
	s_nop 0
	v_cndmask_b32_e32 v23, 0, v23, vcc
	v_cndmask_b32_e32 v22, 0, v22, vcc
	v_cndmask_b32_e32 v21, 0, v21, vcc
	v_cndmask_b32_e32 v20, 0, v20, vcc
	v_add_u32_e32 v206, s18, v139
	v_cmp_gt_u32_e32 vcc, s15, v206
	s_waitcnt vmcnt(9)
	s_nop 0
	v_cndmask_b32_e32 v27, 0, v27, vcc
	v_cndmask_b32_e32 v26, 0, v26, vcc
	v_cndmask_b32_e32 v25, 0, v25, vcc
	v_cndmask_b32_e32 v24, 0, v24, vcc
	v_add_u32_e32 v206, s18, v140
	v_cmp_gt_u32_e32 vcc, s15, v206
	s_waitcnt vmcnt(8)
	s_nop 0
	v_cndmask_b32_e32 v31, 0, v31, vcc
	v_cndmask_b32_e32 v30, 0, v30, vcc
	v_cndmask_b32_e32 v29, 0, v29, vcc
	v_cndmask_b32_e32 v28, 0, v28, vcc
	v_add_u32_e32 v206, s18, v141
	v_cmp_gt_u32_e32 vcc, s15, v206
	s_waitcnt vmcnt(7)
	s_nop 0
	v_cndmask_b32_e32 v35, 0, v35, vcc
	v_cndmask_b32_e32 v34, 0, v34, vcc
	v_cndmask_b32_e32 v33, 0, v33, vcc
	v_cndmask_b32_e32 v32, 0, v32, vcc
	v_add_u32_e32 v206, s18, v142
	v_cmp_gt_u32_e32 vcc, s15, v206
	s_waitcnt vmcnt(6)
	s_nop 0
	v_cndmask_b32_e32 v39, 0, v39, vcc
	v_cndmask_b32_e32 v38, 0, v38, vcc
	v_cndmask_b32_e32 v37, 0, v37, vcc
	v_cndmask_b32_e32 v36, 0, v36, vcc
	v_add_u32_e32 v206, s18, v143
	v_cmp_gt_u32_e32 vcc, s15, v206
	s_waitcnt vmcnt(5)
	s_nop 0
	v_cndmask_b32_e32 v43, 0, v43, vcc
	v_cndmask_b32_e32 v42, 0, v42, vcc
	v_cndmask_b32_e32 v41, 0, v41, vcc
	v_cndmask_b32_e32 v40, 0, v40, vcc
	v_add_u32_e32 v206, s18, v144
	v_cmp_gt_u32_e32 vcc, s15, v206
	s_waitcnt vmcnt(4)
	s_nop 0
	v_cndmask_b32_e32 v47, 0, v47, vcc
	v_cndmask_b32_e32 v46, 0, v46, vcc
	v_cndmask_b32_e32 v45, 0, v45, vcc
	v_cndmask_b32_e32 v44, 0, v44, vcc
	v_add_u32_e32 v206, s18, v145
	v_cmp_gt_u32_e32 vcc, s15, v206
	s_waitcnt vmcnt(3)
	s_nop 0
	v_cndmask_b32_e32 v51, 0, v51, vcc
	v_cndmask_b32_e32 v50, 0, v50, vcc
	v_cndmask_b32_e32 v49, 0, v49, vcc
	v_cndmask_b32_e32 v48, 0, v48, vcc
	v_add_u32_e32 v206, s18, v146
	v_cmp_gt_u32_e32 vcc, s15, v206
	s_waitcnt vmcnt(2)
	s_nop 0
	v_cndmask_b32_e32 v55, 0, v55, vcc
	v_cndmask_b32_e32 v54, 0, v54, vcc
	v_cndmask_b32_e32 v53, 0, v53, vcc
	v_cndmask_b32_e32 v52, 0, v52, vcc
	v_add_u32_e32 v206, s18, v147
	v_cmp_gt_u32_e32 vcc, s15, v206
	s_waitcnt vmcnt(1)
	s_nop 0
	v_cndmask_b32_e32 v61, 0, v61, vcc
	v_cndmask_b32_e32 v60, 0, v60, vcc
	v_cndmask_b32_e32 v59, 0, v59, vcc
	v_cndmask_b32_e32 v58, 0, v58, vcc
	v_add_u32_e32 v206, s18, v148
	v_cmp_gt_u32_e32 vcc, s15, v206
	s_waitcnt vmcnt(0)
	s_nop 0
	v_cndmask_b32_e32 v65, 0, v65, vcc
	v_cndmask_b32_e32 v64, 0, v64, vcc
	v_cndmask_b32_e32 v63, 0, v63, vcc
	v_cndmask_b32_e32 v62, 0, v62, vcc
	v_or_b32_e32 v56, s11, v136
	ds_write_b128 v150, v[0:3]
	ds_write_b128 v150, v[4:7] offset:1056
	ds_write_b128 v150, v[8:11] offset:2112
	ds_write_b128 v150, v[12:15] offset:3168
	ds_write_b128 v150, v[16:19] offset:4224
	ds_write_b128 v150, v[20:23] offset:5280
	ds_write_b128 v150, v[24:27] offset:6336
	ds_write_b128 v150, v[28:31] offset:7392
	ds_write_b128 v150, v[32:35] offset:8448
	ds_write_b128 v150, v[36:39] offset:9504
	ds_write_b128 v150, v[40:43] offset:10560
	ds_write_b128 v150, v[44:47] offset:11616
	ds_write_b128 v150, v[48:51] offset:12672
	ds_write_b128 v150, v[52:55] offset:13728
	ds_write_b128 v150, v[58:61] offset:14784
	ds_write_b128 v150, v[62:65] offset:15840
	v_add_u32_e32 v0, s9, v136
	v_ashrrev_i32_e32 v1, 31, v0
	v_lshlrev_b64 v[134:135], 11, v[0:1]
	v_max_i32_e32 v0, 1, v56
	v_min_i32_e32 v1, 0x1fff, v56
	v_sub_u32_e32 v0, v1, v0
	v_add_u32_e32 v0, 2, v0
	v_cvt_f32_i32_e32 v0, v0
	s_waitcnt lgkmcnt(0)
	s_add_i32 s9, s9, s17
	s_cmpk_lt_i32 s0, 0x1000
	v_div_scale_f32 v1, s[18:19], v0, v0, 1.0
	v_rcp_f32_e32 v2, v1
	s_nop 0
	v_fma_f32 v3, -v1, v2, 1.0
	v_fmac_f32_e32 v2, v3, v2
	v_div_scale_f32 v3, vcc, 1.0, v0, 1.0
	v_mul_f32_e32 v4, v3, v2
	v_fma_f32 v5, -v1, v4, v3
	v_fmac_f32_e32 v4, v5, v2
	v_fma_f32 v1, -v1, v4, v3
	v_div_fmas_f32 v1, v1, v2, v4
	v_div_fixup_f32 v20, v1, v0, 1.0
	ds_read_b128 v[0:3], v149 offset:3696
	s_waitcnt lgkmcnt(0)
	v_lshlrev_b32_e32 v4, 16, v0
	v_and_b32_e32 v0, 0xffff0000, v0
	v_lshlrev_b32_e32 v5, 16, v1
	v_and_b32_e32 v1, 0xffff0000, v1
	v_lshlrev_b32_e32 v6, 16, v2
	v_and_b32_e32 v2, 0xffff0000, v2
	v_lshlrev_b32_e32 v7, 16, v3
	v_and_b32_e32 v3, 0xffff0000, v3
	v_add_f32_e32 v8, 0, v0
	v_add_f32_e32 v9, 0, v1
	v_add_f32_e32 v10, 0, v2
	v_add_f32_e32 v11, 0, v3
	ds_read_b128 v[0:3], v149 offset:4224
	v_add_f32_e32 v4, 0, v4
	v_add_f32_e32 v5, 0, v5
	v_add_f32_e32 v6, 0, v6
	v_add_f32_e32 v7, 0, v7
	s_waitcnt lgkmcnt(0)
	v_lshlrev_b32_e32 v12, 16, v0
	v_and_b32_e32 v0, 0xffff0000, v0
	v_lshlrev_b32_e32 v13, 16, v1
	v_and_b32_e32 v1, 0xffff0000, v1
	v_lshlrev_b32_e32 v14, 16, v2
	v_and_b32_e32 v2, 0xffff0000, v2
	v_lshlrev_b32_e32 v15, 16, v3
	v_and_b32_e32 v3, 0xffff0000, v3
	v_add_f32_e32 v8, v8, v0
	v_add_f32_e32 v9, v9, v1
	v_add_f32_e32 v10, v10, v2
	v_add_f32_e32 v11, v11, v3
	v_add_f32_e32 v4, v4, v12
	v_add_f32_e32 v5, v5, v13
	v_add_f32_e32 v6, v6, v14
	v_add_f32_e32 v7, v7, v15
	v_fma_f32 v0, v20, v8, -v0
	v_fma_f32 v1, v20, v9, -v1
	v_fma_f32 v2, v20, v10, -v2
	v_fma_f32 v3, v20, v11, -v3
	v_fma_f32 v4, v20, v4, -v12
	v_fma_f32 v5, v20, v5, -v13
	v_fma_f32 v6, v20, v6, -v14
	v_fma_f32 v7, v20, v7, -v15
	v_cvt_pk_bf16_f32 v0, v4, v0
	v_cvt_pk_bf16_f32 v1, v5, v1
	v_cvt_pk_bf16_f32 v2, v6, v2
	v_cvt_pk_bf16_f32 v3, v7, v3
	s_waitcnt vmcnt(2)
	v_mfma_f32_16x16x32_bf16 v[16:19], v[90:93], v[0:3], 0
	s_waitcnt vmcnt(2)
	v_mfma_f32_16x16x32_bf16 v[4:7], v[94:97], v[0:3], 0
	s_waitcnt vmcnt(1)
	v_mfma_f32_16x16x32_bf16 v[8:11], v[106:109], v[0:3], 0
	s_waitcnt vmcnt(0)
	v_mfma_f32_16x16x32_bf16 v[0:3], v[110:113], v[0:3], 0
	global_load_dwordx4 v[90:93], v[86:87], off
	global_load_dwordx4 v[94:97], v[82:83], off
	global_load_dwordx4 v[106:109], v[84:85], off
	global_load_dwordx4 v[110:113], v[88:89], off
	ds_read_b128 v[12:15], v149 offset:3760
	s_waitcnt lgkmcnt(0)
	v_lshlrev_b32_e32 v21, 16, v12
	v_and_b32_e32 v12, 0xffff0000, v12
	v_lshlrev_b32_e32 v22, 16, v13
	v_and_b32_e32 v13, 0xffff0000, v13
	v_lshlrev_b32_e32 v23, 16, v14
	v_and_b32_e32 v14, 0xffff0000, v14
	v_lshlrev_b32_e32 v24, 16, v15
	v_and_b32_e32 v15, 0xffff0000, v15
	v_add_f32_e32 v25, 0, v12
	v_add_f32_e32 v26, 0, v13
	v_add_f32_e32 v27, 0, v14
	v_add_f32_e32 v28, 0, v15
	ds_read_b128 v[12:15], v149 offset:4288
	v_add_f32_e32 v21, 0, v21
	v_add_f32_e32 v22, 0, v22
	v_add_f32_e32 v23, 0, v23
	v_add_f32_e32 v24, 0, v24
	s_waitcnt lgkmcnt(0)
	v_lshlrev_b32_e32 v29, 16, v12
	v_and_b32_e32 v12, 0xffff0000, v12
	v_lshlrev_b32_e32 v30, 16, v13
	v_and_b32_e32 v13, 0xffff0000, v13
	v_lshlrev_b32_e32 v31, 16, v14
	v_and_b32_e32 v14, 0xffff0000, v14
	v_lshlrev_b32_e32 v32, 16, v15
	v_and_b32_e32 v15, 0xffff0000, v15
	v_add_f32_e32 v21, v21, v29
	v_add_f32_e32 v25, v25, v12
	v_add_f32_e32 v22, v22, v30
	v_add_f32_e32 v26, v26, v13
	v_add_f32_e32 v23, v23, v31
	v_add_f32_e32 v27, v27, v14
	v_add_f32_e32 v28, v28, v15
	v_add_f32_e32 v24, v24, v32
	v_fma_f32 v21, v20, v21, -v29
	v_fma_f32 v12, v20, v25, -v12
	v_fma_f32 v22, v20, v22, -v30
	v_fma_f32 v13, v20, v26, -v13
	v_fma_f32 v23, v20, v23, -v31
	v_fma_f32 v14, v20, v27, -v14
	v_fma_f32 v15, v20, v28, -v15
	v_fma_f32 v24, v20, v24, -v32
	v_cvt_pk_bf16_f32 v20, v21, v12
	v_cvt_pk_bf16_f32 v21, v22, v13
	v_cvt_pk_bf16_f32 v22, v23, v14
	v_cvt_pk_bf16_f32 v23, v24, v15
	s_waitcnt vmcnt(0)
	v_mfma_f32_16x16x32_bf16 v[12:15], v[166:169], v[20:23], v[4:7]
	s_nop 2
	s_waitcnt vmcnt(0)
	v_mfma_f32_16x16x32_bf16 v[8:11], v[170:173], v[20:23], v[8:11]
	s_waitcnt vmcnt(0)
	v_mfma_f32_16x16x32_bf16 v[4:7], v[174:177], v[20:23], v[16:19]
	s_nop 2
	s_waitcnt vmcnt(0)
	v_mfma_f32_16x16x32_bf16 v[0:3], v[178:181], v[20:23], v[0:3]
	v_max_i32_e32 v16, 2, v56
	v_min_i32_e32 v17, 0x1ffe, v56
	v_sub_u32_e32 v16, v17, v16
	v_add_u32_e32 v16, 4, v16
	v_cvt_f32_i32_e32 v16, v16
	v_div_scale_f32 v17, s[18:19], v16, v16, 1.0
	v_rcp_f32_e32 v18, v17
	s_nop 0
	v_fma_f32 v19, -v17, v18, 1.0
	v_fmac_f32_e32 v18, v19, v18
	v_div_scale_f32 v19, vcc, 1.0, v16, 1.0
	v_mul_f32_e32 v20, v19, v18
	v_fma_f32 v21, -v17, v20, v19
	v_fmac_f32_e32 v20, v21, v18
	v_fma_f32 v17, -v17, v20, v19
	v_div_fmas_f32 v17, v17, v18, v20
	v_div_fixup_f32 v36, v17, v16, 1.0
	ds_read_b128 v[16:19], v149 offset:3296
	s_waitcnt lgkmcnt(0)
	v_lshlrev_b32_e32 v20, 16, v16
	v_and_b32_e32 v16, 0xffff0000, v16
	v_lshlrev_b32_e32 v21, 16, v17
	v_and_b32_e32 v17, 0xffff0000, v17
	v_lshlrev_b32_e32 v22, 16, v18
	v_and_b32_e32 v18, 0xffff0000, v18
	v_lshlrev_b32_e32 v23, 16, v19
	v_and_b32_e32 v19, 0xffff0000, v19
	v_add_f32_e32 v24, 0, v16
	v_add_f32_e32 v25, 0, v17
	v_add_f32_e32 v26, 0, v18
	v_add_f32_e32 v27, 0, v19
	ds_read_b128 v[16:19], v149 offset:3824
	v_add_f32_e32 v20, 0, v20
	v_add_f32_e32 v21, 0, v21
	v_add_f32_e32 v22, 0, v22
	v_add_f32_e32 v23, 0, v23
	s_waitcnt lgkmcnt(0)
	v_lshlrev_b32_e32 v28, 16, v16
	v_and_b32_e32 v16, 0xffff0000, v16
	v_lshlrev_b32_e32 v29, 16, v17
	v_and_b32_e32 v17, 0xffff0000, v17
	v_lshlrev_b32_e32 v30, 16, v18
	v_and_b32_e32 v18, 0xffff0000, v18
	v_lshlrev_b32_e32 v31, 16, v19
	v_and_b32_e32 v19, 0xffff0000, v19
	v_add_f32_e32 v24, v24, v16
	v_add_f32_e32 v25, v25, v17
	v_add_f32_e32 v26, v26, v18
	v_add_f32_e32 v27, v27, v19
	ds_read_b128 v[16:19], v149 offset:4352
	v_add_f32_e32 v20, v20, v28
	v_add_f32_e32 v21, v21, v29
	v_add_f32_e32 v22, v22, v30
	v_add_f32_e32 v23, v23, v31
	s_waitcnt lgkmcnt(0)
	v_lshlrev_b32_e32 v28, 16, v16
	v_and_b32_e32 v29, 0xffff0000, v16
	v_lshlrev_b32_e32 v30, 16, v17
	v_and_b32_e32 v31, 0xffff0000, v17
	v_lshlrev_b32_e32 v32, 16, v18
	v_and_b32_e32 v33, 0xffff0000, v18
	v_lshlrev_b32_e32 v34, 16, v19
	v_and_b32_e32 v35, 0xffff0000, v19
	ds_read_b128 v[16:19], v149 offset:4880
	v_add_f32_e32 v24, v24, v29
	v_add_f32_e32 v25, v25, v31
	v_add_f32_e32 v26, v26, v33
	v_add_f32_e32 v27, v27, v35
	s_waitcnt lgkmcnt(0)
	v_lshlrev_b32_e32 v37, 16, v16
	v_and_b32_e32 v16, 0xffff0000, v16
	v_lshlrev_b32_e32 v38, 16, v17
	v_and_b32_e32 v17, 0xffff0000, v17
	v_lshlrev_b32_e32 v39, 16, v18
	v_and_b32_e32 v18, 0xffff0000, v18
	v_lshlrev_b32_e32 v40, 16, v19
	v_and_b32_e32 v19, 0xffff0000, v19
	v_add_f32_e32 v20, v20, v28
	v_add_f32_e32 v21, v21, v30
	v_add_f32_e32 v22, v22, v32
	v_add_f32_e32 v23, v23, v34
	v_add_f32_e32 v16, v24, v16
	v_add_f32_e32 v17, v25, v17
	v_add_f32_e32 v18, v26, v18
	v_add_f32_e32 v19, v27, v19
	v_add_f32_e32 v20, v20, v37
	v_add_f32_e32 v21, v21, v38
	v_add_f32_e32 v22, v22, v39
	v_add_f32_e32 v23, v23, v40
	v_fma_f32 v16, v36, v16, -v29
	v_fma_f32 v17, v36, v17, -v31
	v_fma_f32 v18, v36, v18, -v33
	v_fma_f32 v19, v36, v19, -v35
	v_fma_f32 v20, v36, v20, -v28
	v_fma_f32 v21, v36, v21, -v30
	v_fma_f32 v22, v36, v22, -v32
	v_fma_f32 v23, v36, v23, -v34
	v_cvt_pk_bf16_f32 v16, v20, v16
	v_cvt_pk_bf16_f32 v17, v21, v17
	v_cvt_pk_bf16_f32 v18, v22, v18
	v_cvt_pk_bf16_f32 v19, v23, v19
	s_waitcnt vmcnt(2)
	v_mfma_f32_16x16x32_bf16 v[32:35], v[90:93], v[16:19], 0
	s_waitcnt vmcnt(2)
	v_mfma_f32_16x16x32_bf16 v[20:23], v[94:97], v[16:19], 0
	s_waitcnt vmcnt(1)
	v_mfma_f32_16x16x32_bf16 v[24:27], v[106:109], v[16:19], 0
	s_waitcnt vmcnt(0)
	v_mfma_f32_16x16x32_bf16 v[16:19], v[110:113], v[16:19], 0
	global_load_dwordx4 v[90:93], v[98:99], off
	global_load_dwordx4 v[94:97], v[100:101], off
	global_load_dwordx4 v[106:109], v[102:103], off
	global_load_dwordx4 v[110:113], v[104:105], off
	ds_read_b128 v[28:31], v149 offset:3360
	s_waitcnt lgkmcnt(0)
	v_lshlrev_b32_e32 v37, 16, v28
	v_and_b32_e32 v28, 0xffff0000, v28
	v_lshlrev_b32_e32 v38, 16, v29
	v_and_b32_e32 v29, 0xffff0000, v29
	v_lshlrev_b32_e32 v39, 16, v30
	v_and_b32_e32 v30, 0xffff0000, v30
	v_lshlrev_b32_e32 v40, 16, v31
	v_and_b32_e32 v31, 0xffff0000, v31
	v_add_f32_e32 v41, 0, v28
	v_add_f32_e32 v42, 0, v29
	v_add_f32_e32 v43, 0, v30
	v_add_f32_e32 v44, 0, v31
	ds_read_b128 v[28:31], v149 offset:3888
	v_add_f32_e32 v37, 0, v37
	v_add_f32_e32 v38, 0, v38
	v_add_f32_e32 v39, 0, v39
	v_add_f32_e32 v40, 0, v40
	s_waitcnt lgkmcnt(0)
	v_lshlrev_b32_e32 v45, 16, v28
	v_and_b32_e32 v28, 0xffff0000, v28
	v_lshlrev_b32_e32 v46, 16, v29
	v_and_b32_e32 v29, 0xffff0000, v29
	v_lshlrev_b32_e32 v47, 16, v30
	v_and_b32_e32 v30, 0xffff0000, v30
	v_lshlrev_b32_e32 v48, 16, v31
	v_and_b32_e32 v31, 0xffff0000, v31
	v_add_f32_e32 v41, v41, v28
	v_add_f32_e32 v42, v42, v29
	v_add_f32_e32 v43, v43, v30
	v_add_f32_e32 v44, v44, v31
	ds_read_b128 v[28:31], v149 offset:4416
	v_add_f32_e32 v37, v37, v45
	v_add_f32_e32 v38, v38, v46
	v_add_f32_e32 v39, v39, v47
	v_add_f32_e32 v40, v40, v48
	s_waitcnt lgkmcnt(0)
	v_lshlrev_b32_e32 v45, 16, v28
	v_and_b32_e32 v46, 0xffff0000, v28
	v_lshlrev_b32_e32 v47, 16, v29
	v_and_b32_e32 v48, 0xffff0000, v29
	v_lshlrev_b32_e32 v49, 16, v30
	v_and_b32_e32 v50, 0xffff0000, v30
	v_lshlrev_b32_e32 v51, 16, v31
	v_and_b32_e32 v52, 0xffff0000, v31
	ds_read_b128 v[28:31], v149 offset:4944
	v_add_f32_e32 v37, v37, v45
	v_add_f32_e32 v41, v41, v46
	v_add_f32_e32 v38, v38, v47
	v_add_f32_e32 v42, v42, v48
	v_add_f32_e32 v39, v39, v49
	v_add_f32_e32 v43, v43, v50
	v_add_f32_e32 v44, v44, v52
	s_waitcnt lgkmcnt(0)
	v_lshlrev_b32_e32 v53, 16, v28
	v_and_b32_e32 v28, 0xffff0000, v28
	v_lshlrev_b32_e32 v54, 16, v29
	v_and_b32_e32 v29, 0xffff0000, v29
	v_lshlrev_b32_e32 v55, 16, v30
	v_and_b32_e32 v30, 0xffff0000, v30
	v_lshlrev_b32_e32 v57, 16, v31
	v_and_b32_e32 v31, 0xffff0000, v31
	v_add_f32_e32 v40, v40, v51
	v_add_f32_e32 v37, v37, v53
	v_add_f32_e32 v28, v41, v28
	v_add_f32_e32 v38, v38, v54
	v_add_f32_e32 v29, v42, v29
	v_add_f32_e32 v39, v39, v55
	v_add_f32_e32 v30, v43, v30
	v_add_f32_e32 v31, v44, v31
	v_add_f32_e32 v40, v40, v57
	v_fma_f32 v37, v36, v37, -v45
	v_fma_f32 v28, v36, v28, -v46
	v_fma_f32 v38, v36, v38, -v47
	v_fma_f32 v29, v36, v29, -v48
	v_fma_f32 v39, v36, v39, -v49
	v_fma_f32 v30, v36, v30, -v50
	v_fma_f32 v31, v36, v31, -v52
	v_fma_f32 v40, v36, v40, -v51
	v_cvt_pk_bf16_f32 v36, v37, v28
	v_cvt_pk_bf16_f32 v37, v38, v29
	v_cvt_pk_bf16_f32 v38, v39, v30
	v_cvt_pk_bf16_f32 v39, v40, v31
	s_waitcnt vmcnt(0)
	v_mfma_f32_16x16x32_bf16 v[28:31], v[182:185], v[36:39], v[20:23]
	s_nop 2
	s_waitcnt vmcnt(0)
	v_mfma_f32_16x16x32_bf16 v[24:27], v[186:189], v[36:39], v[24:27]
	s_waitcnt vmcnt(0)
	v_mfma_f32_16x16x32_bf16 v[20:23], v[190:193], v[36:39], v[32:35]
	s_nop 2
	s_waitcnt vmcnt(0)
	v_mfma_f32_16x16x32_bf16 v[16:19], v[194:197], v[36:39], v[16:19]
	v_max_i32_e32 v32, 4, v56
	v_min_i32_e32 v33, 0x1ffc, v56
	v_sub_u32_e32 v32, v33, v32
	v_add_u32_e32 v32, 8, v32
	v_cvt_f32_i32_e32 v32, v32
	v_div_scale_f32 v33, s[18:19], v32, v32, 1.0
	v_rcp_f32_e32 v34, v33
	s_nop 0
	v_fma_f32 v35, -v33, v34, 1.0
	v_fmac_f32_e32 v34, v35, v34
	v_div_scale_f32 v35, vcc, 1.0, v32, 1.0
	v_mul_f32_e32 v36, v35, v34
	v_fma_f32 v37, -v33, v36, v35
	v_fmac_f32_e32 v36, v37, v34
	v_fma_f32 v33, -v33, v36, v35
	v_div_fmas_f32 v33, v33, v34, v36
	v_div_fixup_f32 v40, v33, v32, 1.0
	ds_read_b128 v[32:35], v149 offset:2368
	s_waitcnt lgkmcnt(0)
	v_lshlrev_b32_e32 v36, 16, v32
	v_and_b32_e32 v32, 0xffff0000, v32
	v_lshlrev_b32_e32 v37, 16, v33
	v_and_b32_e32 v33, 0xffff0000, v33
	v_lshlrev_b32_e32 v38, 16, v34
	v_and_b32_e32 v34, 0xffff0000, v34
	v_lshlrev_b32_e32 v39, 16, v35
	v_and_b32_e32 v35, 0xffff0000, v35
	v_add_f32_e32 v41, 0, v32
	v_add_f32_e32 v42, 0, v33
	v_add_f32_e32 v43, 0, v34
	v_add_f32_e32 v44, 0, v35
	ds_read_b128 v[32:35], v149 offset:2896
	v_add_f32_e32 v36, 0, v36
	v_add_f32_e32 v37, 0, v37
	v_add_f32_e32 v38, 0, v38
	v_add_f32_e32 v39, 0, v39
	s_waitcnt lgkmcnt(0)
	v_lshlrev_b32_e32 v45, 16, v32
	v_and_b32_e32 v32, 0xffff0000, v32
	v_lshlrev_b32_e32 v46, 16, v33
	v_and_b32_e32 v33, 0xffff0000, v33
	v_lshlrev_b32_e32 v47, 16, v34
	v_and_b32_e32 v34, 0xffff0000, v34
	v_lshlrev_b32_e32 v48, 16, v35
	v_and_b32_e32 v35, 0xffff0000, v35
	v_add_f32_e32 v41, v41, v32
	v_add_f32_e32 v42, v42, v33
	v_add_f32_e32 v43, v43, v34
	v_add_f32_e32 v44, v44, v35
	ds_read_b128 v[32:35], v149 offset:3424
	v_add_f32_e32 v36, v36, v45
	v_add_f32_e32 v37, v37, v46
	v_add_f32_e32 v38, v38, v47
	v_add_f32_e32 v39, v39, v48
	s_waitcnt lgkmcnt(0)
	v_lshlrev_b32_e32 v45, 16, v32
	v_and_b32_e32 v32, 0xffff0000, v32
	v_lshlrev_b32_e32 v46, 16, v33
	v_and_b32_e32 v33, 0xffff0000, v33
	v_lshlrev_b32_e32 v47, 16, v34
	v_and_b32_e32 v34, 0xffff0000, v34
	v_lshlrev_b32_e32 v48, 16, v35
	v_and_b32_e32 v35, 0xffff0000, v35
	v_add_f32_e32 v41, v41, v32
	v_add_f32_e32 v42, v42, v33
	v_add_f32_e32 v43, v43, v34
	v_add_f32_e32 v44, v44, v35
	ds_read_b128 v[32:35], v149 offset:3952
	v_add_f32_e32 v36, v36, v45
	v_add_f32_e32 v37, v37, v46
	v_add_f32_e32 v38, v38, v47
	v_add_f32_e32 v39, v39, v48
	s_waitcnt lgkmcnt(0)
	v_lshlrev_b32_e32 v45, 16, v32
	v_lshlrev_b32_e32 v46, 16, v33
	v_lshlrev_b32_e32 v47, 16, v34
	v_lshlrev_b32_e32 v48, 16, v35
	v_add_f32_e32 v45, v36, v45
	v_add_f32_e32 v46, v37, v46
	v_add_f32_e32 v47, v38, v47
	v_add_f32_e32 v48, v39, v48
	ds_read_b128 v[36:39], v149 offset:4480
	v_and_b32_e32 v32, 0xffff0000, v32
	v_and_b32_e32 v33, 0xffff0000, v33
	v_and_b32_e32 v34, 0xffff0000, v34
	v_and_b32_e32 v35, 0xffff0000, v35
	v_add_f32_e32 v41, v41, v32
	v_add_f32_e32 v42, v42, v33
	v_add_f32_e32 v43, v43, v34
	v_add_f32_e32 v44, v44, v35
	s_waitcnt lgkmcnt(0)
	v_lshlrev_b32_e32 v32, 16, v36
	v_and_b32_e32 v33, 0xffff0000, v36
	v_lshlrev_b32_e32 v34, 16, v37
	v_and_b32_e32 v35, 0xffff0000, v37
	v_lshlrev_b32_e32 v36, 16, v38
	v_and_b32_e32 v37, 0xffff0000, v38
	v_lshlrev_b32_e32 v38, 16, v39
	v_and_b32_e32 v39, 0xffff0000, v39
	v_add_f32_e32 v49, v45, v32
	v_add_f32_e32 v50, v42, v35
	v_add_f32_e32 v51, v43, v37
	v_add_f32_e32 v52, v44, v39
	ds_read_b128 v[42:45], v149 offset:5008
	v_add_f32_e32 v41, v41, v33
	v_add_f32_e32 v46, v46, v34
	v_add_f32_e32 v47, v47, v36
	v_add_f32_e32 v48, v48, v38
	s_waitcnt lgkmcnt(0)
	v_lshlrev_b32_e32 v53, 16, v42
	v_and_b32_e32 v42, 0xffff0000, v42
	v_lshlrev_b32_e32 v54, 16, v43
	v_and_b32_e32 v43, 0xffff0000, v43
	v_lshlrev_b32_e32 v55, 16, v44
	v_and_b32_e32 v44, 0xffff0000, v44
	v_lshlrev_b32_e32 v57, 16, v45
	v_and_b32_e32 v45, 0xffff0000, v45
	v_add_f32_e32 v49, v49, v53
	v_add_f32_e32 v53, v41, v42
	v_add_f32_e32 v50, v50, v43
	v_add_f32_e32 v51, v51, v44
	v_add_f32_e32 v52, v52, v45
	ds_read_b128 v[42:45], v149 offset:5536
	v_add_f32_e32 v46, v46, v54
	v_add_f32_e32 v47, v47, v55
	v_add_f32_e32 v48, v48, v57
	s_waitcnt lgkmcnt(0)
	v_lshlrev_b32_e32 v41, 16, v42
	v_and_b32_e32 v42, 0xffff0000, v42
	v_lshlrev_b32_e32 v54, 16, v43
	v_and_b32_e32 v55, 0xffff0000, v43
	v_lshlrev_b32_e32 v57, 16, v44
	v_and_b32_e32 v58, 0xffff0000, v44
	v_lshlrev_b32_e32 v59, 16, v45
	v_and_b32_e32 v60, 0xffff0000, v45
	v_add_f32_e32 v42, v53, v42
	v_add_f32_e32 v43, v46, v54
	v_add_f32_e32 v44, v50, v55
	v_add_f32_e32 v45, v47, v57
	v_add_f32_e32 v46, v51, v58
	v_add_f32_e32 v47, v48, v59
	v_add_f32_e32 v48, v52, v60
	ds_read_b128 v[50:53], v149 offset:6064
	v_add_f32_e32 v41, v49, v41
	s_waitcnt lgkmcnt(0)
	v_lshlrev_b32_e32 v49, 16, v50
	v_and_b32_e32 v50, 0xffff0000, v50
	v_lshlrev_b32_e32 v54, 16, v51
	v_and_b32_e32 v51, 0xffff0000, v51
	v_lshlrev_b32_e32 v55, 16, v52
	v_and_b32_e32 v52, 0xffff0000, v52
	v_lshlrev_b32_e32 v57, 16, v53
	v_and_b32_e32 v53, 0xffff0000, v53
	v_add_f32_e32 v41, v41, v49
	v_add_f32_e32 v42, v42, v50
	v_add_f32_e32 v43, v43, v54
	v_add_f32_e32 v44, v44, v51
	v_add_f32_e32 v45, v45, v55
	v_add_f32_e32 v46, v46, v52
	v_add_f32_e32 v47, v47, v57
	v_add_f32_e32 v48, v48, v53
	v_fma_f32 v32, v40, v41, -v32
	v_fma_f32 v33, v40, v42, -v33
	v_fma_f32 v34, v40, v43, -v34
	v_fma_f32 v35, v40, v44, -v35
	v_fma_f32 v36, v40, v45, -v36
	v_fma_f32 v37, v40, v46, -v37
	v_fma_f32 v38, v40, v47, -v38
	v_fma_f32 v39, v40, v48, -v39
	v_cvt_pk_bf16_f32 v42, v32, v33
	v_cvt_pk_bf16_f32 v43, v34, v35
	v_cvt_pk_bf16_f32 v44, v36, v37
	v_cvt_pk_bf16_f32 v45, v38, v39
	s_waitcnt vmcnt(3)
	v_mfma_f32_16x16x32_bf16 v[32:35], v[90:93], v[42:45], 0
	s_waitcnt vmcnt(2)
	v_mfma_f32_16x16x32_bf16 v[36:39], v[94:97], v[42:45], 0
	s_waitcnt vmcnt(1)
	v_mfma_f32_16x16x32_bf16 v[48:51], v[106:109], v[42:45], 0
	s_waitcnt vmcnt(0)
	v_mfma_f32_16x16x32_bf16 v[52:55], v[110:113], v[42:45], 0
	global_load_dwordx4 v[90:93], v[114:115], off
	global_load_dwordx4 v[94:97], v[116:117], off
	global_load_dwordx4 v[106:109], v[118:119], off
	global_load_dwordx4 v[110:113], v[120:121], off
	ds_read_b128 v[42:45], v149 offset:2432
	s_waitcnt lgkmcnt(0)
	v_lshlrev_b32_e32 v41, 16, v42
	v_and_b32_e32 v42, 0xffff0000, v42
	v_lshlrev_b32_e32 v46, 16, v43
	v_and_b32_e32 v43, 0xffff0000, v43
	v_lshlrev_b32_e32 v47, 16, v44
	v_and_b32_e32 v44, 0xffff0000, v44
	v_lshlrev_b32_e32 v57, 16, v45
	v_and_b32_e32 v45, 0xffff0000, v45
	v_add_f32_e32 v58, 0, v42
	v_add_f32_e32 v59, 0, v43
	v_add_f32_e32 v60, 0, v44
	v_add_f32_e32 v61, 0, v45
	ds_read_b128 v[42:45], v149 offset:2960
	v_add_f32_e32 v41, 0, v41
	v_add_f32_e32 v46, 0, v46
	v_add_f32_e32 v47, 0, v47
	v_add_f32_e32 v57, 0, v57
	s_waitcnt lgkmcnt(0)
	v_lshlrev_b32_e32 v62, 16, v42
	v_and_b32_e32 v42, 0xffff0000, v42
	v_lshlrev_b32_e32 v63, 16, v43
	v_and_b32_e32 v43, 0xffff0000, v43
	v_lshlrev_b32_e32 v64, 16, v44
	v_and_b32_e32 v44, 0xffff0000, v44
	v_lshlrev_b32_e32 v65, 16, v45
	v_and_b32_e32 v45, 0xffff0000, v45
	v_add_f32_e32 v58, v58, v42
	v_add_f32_e32 v59, v59, v43
	v_add_f32_e32 v60, v60, v44
	v_add_f32_e32 v61, v61, v45
	ds_read_b128 v[42:45], v149 offset:3488
	v_add_f32_e32 v41, v41, v62
	v_add_f32_e32 v46, v46, v63
	v_add_f32_e32 v47, v47, v64
	v_add_f32_e32 v57, v57, v65
	s_waitcnt lgkmcnt(0)
	v_lshlrev_b32_e32 v62, 16, v42
	v_and_b32_e32 v42, 0xffff0000, v42
	v_lshlrev_b32_e32 v63, 16, v43
	v_and_b32_e32 v43, 0xffff0000, v43
	v_lshlrev_b32_e32 v64, 16, v44
	v_and_b32_e32 v44, 0xffff0000, v44
	v_lshlrev_b32_e32 v65, 16, v45
	v_and_b32_e32 v45, 0xffff0000, v45
	v_add_f32_e32 v58, v58, v42
	v_add_f32_e32 v59, v59, v43
	v_add_f32_e32 v60, v60, v44
	v_add_f32_e32 v61, v61, v45
	ds_read_b128 v[42:45], v149 offset:4016
	v_add_f32_e32 v41, v41, v62
	v_add_f32_e32 v46, v46, v63
	v_add_f32_e32 v47, v47, v64
	v_add_f32_e32 v57, v57, v65
	s_waitcnt lgkmcnt(0)
	v_lshlrev_b32_e32 v62, 16, v42
	v_and_b32_e32 v42, 0xffff0000, v42
	v_lshlrev_b32_e32 v63, 16, v43
	v_and_b32_e32 v43, 0xffff0000, v43
	v_lshlrev_b32_e32 v64, 16, v44
	v_and_b32_e32 v44, 0xffff0000, v44
	v_lshlrev_b32_e32 v65, 16, v45
	v_and_b32_e32 v45, 0xffff0000, v45
	v_add_f32_e32 v66, v58, v42
	v_add_f32_e32 v67, v59, v43
	v_add_f32_e32 v68, v60, v44
	v_add_f32_e32 v69, v61, v45
	ds_read_b128 v[58:61], v149 offset:4544
	v_add_f32_e32 v62, v41, v62
	v_add_f32_e32 v63, v46, v63
	v_add_f32_e32 v64, v47, v64
	v_add_f32_e32 v65, v57, v65
	s_waitcnt lgkmcnt(0)
	v_lshlrev_b32_e32 v41, 16, v58
	v_and_b32_e32 v42, 0xffff0000, v58
	v_lshlrev_b32_e32 v43, 16, v59
	v_and_b32_e32 v44, 0xffff0000, v59
	v_lshlrev_b32_e32 v45, 16, v60
	v_and_b32_e32 v46, 0xffff0000, v60
	v_lshlrev_b32_e32 v47, 16, v61
	v_and_b32_e32 v57, 0xffff0000, v61
	ds_read_b128 v[58:61], v149 offset:5072
	v_add_f32_e32 v66, v66, v42
	v_add_f32_e32 v67, v67, v44
	v_add_f32_e32 v68, v68, v46
	v_add_f32_e32 v69, v69, v57
	s_waitcnt lgkmcnt(0)
	v_lshlrev_b32_e32 v70, 16, v58
	v_and_b32_e32 v58, 0xffff0000, v58
	v_lshlrev_b32_e32 v71, 16, v59
	v_and_b32_e32 v59, 0xffff0000, v59
	v_lshlrev_b32_e32 v131, 16, v60
	v_and_b32_e32 v60, 0xffff0000, v60
	v_lshlrev_b32_e32 v133, 16, v61
	v_and_b32_e32 v61, 0xffff0000, v61
	v_add_f32_e32 v66, v66, v58
	v_add_f32_e32 v67, v67, v59
	v_add_f32_e32 v68, v68, v60
	v_add_f32_e32 v69, v69, v61
	ds_read_b128 v[58:61], v149 offset:5600
	v_add_f32_e32 v62, v62, v41
	v_add_f32_e32 v63, v63, v43
	v_add_f32_e32 v64, v64, v45
	v_add_f32_e32 v65, v65, v47
	v_add_f32_e32 v62, v62, v70
	v_add_f32_e32 v63, v63, v71
	v_add_f32_e32 v64, v64, v131
	v_add_f32_e32 v65, v65, v133
	s_waitcnt lgkmcnt(0)
	v_lshlrev_b32_e32 v70, 16, v58
	v_and_b32_e32 v71, 0xffff0000, v58
	v_lshlrev_b32_e32 v131, 16, v59
	v_and_b32_e32 v133, 0xffff0000, v59
	v_lshlrev_b32_e32 v151, 16, v60
	v_and_b32_e32 v152, 0xffff0000, v60
	v_lshlrev_b32_e32 v153, 16, v61
	v_and_b32_e32 v154, 0xffff0000, v61
	v_add_f32_e32 v58, v62, v70
	v_add_f32_e32 v59, v66, v71
	v_add_f32_e32 v60, v63, v131
	v_add_f32_e32 v61, v67, v133
	v_add_f32_e32 v62, v64, v151
	v_add_f32_e32 v63, v68, v152
	v_add_f32_e32 v64, v65, v153
	v_add_f32_e32 v65, v69, v154
	ds_read_b128 v[66:69], v149 offset:6128
	s_waitcnt lgkmcnt(0)
	v_lshlrev_b32_e32 v70, 16, v66
	v_and_b32_e32 v66, 0xffff0000, v66
	v_lshlrev_b32_e32 v71, 16, v67
	v_and_b32_e32 v67, 0xffff0000, v67
	v_lshlrev_b32_e32 v131, 16, v68
	v_and_b32_e32 v68, 0xffff0000, v68
	v_lshlrev_b32_e32 v133, 16, v69
	v_and_b32_e32 v69, 0xffff0000, v69
	v_add_f32_e32 v58, v58, v70
	v_add_f32_e32 v59, v59, v66
	v_add_f32_e32 v60, v60, v71
	v_add_f32_e32 v61, v61, v67
	v_add_f32_e32 v62, v62, v131
	v_add_f32_e32 v63, v63, v68
	v_add_f32_e32 v64, v64, v133
	v_add_f32_e32 v65, v65, v69
	v_fma_f32 v41, v40, v58, -v41
	v_fma_f32 v42, v40, v59, -v42
	v_fma_f32 v43, v40, v60, -v43
	v_fma_f32 v44, v40, v61, -v44
	v_fma_f32 v45, v40, v62, -v45
	v_fma_f32 v46, v40, v63, -v46
	v_fma_f32 v47, v40, v64, -v47
	v_fma_f32 v40, v40, v65, -v57
	v_cvt_pk_bf16_f32 v58, v41, v42
	v_cvt_pk_bf16_f32 v59, v43, v44
	v_cvt_pk_bf16_f32 v60, v45, v46
	v_cvt_pk_bf16_f32 v61, v47, v40
	s_waitcnt vmcnt(0)
	v_mfma_f32_16x16x32_bf16 v[44:47], v[198:201], v[58:61], v[32:35]
	s_nop 2
	s_waitcnt vmcnt(0)
	v_mfma_f32_16x16x32_bf16 v[40:43], v[202:205], v[58:61], v[36:39]
	s_waitcnt vmcnt(0)
	v_mfma_f32_16x16x32_bf16 v[36:39], v[214:217], v[58:61], v[48:51]
	s_nop 1
	v_max_i32_e32 v48, 8, v56
	v_min_i32_e32 v49, 0x1ff8, v56
	v_sub_u32_e32 v48, v49, v48
	v_add_u32_e32 v48, 16, v48
	v_cvt_f32_i32_e32 v48, v48
	s_waitcnt vmcnt(0)
	v_mfma_f32_16x16x32_bf16 v[32:35], v[218:221], v[58:61], v[52:55]
	v_div_scale_f32 v49, s[18:19], v48, v48, 1.0
	v_rcp_f32_e32 v50, v49
	s_mov_b64 s[18:19], 0x1a000200
	v_fma_f32 v51, -v49, v50, 1.0
	v_fmac_f32_e32 v50, v51, v50
	v_div_scale_f32 v51, vcc, 1.0, v48, 1.0
	v_mul_f32_e32 v52, v51, v50
	v_fma_f32 v53, -v49, v52, v51
	v_fmac_f32_e32 v52, v53, v50
	v_fma_f32 v49, -v49, v52, v51
	v_div_fmas_f32 v49, v49, v50, v52
	v_div_fixup_f32 v56, v49, v48, 1.0
	ds_read_b128 v[48:51], v149 offset:384
	s_waitcnt lgkmcnt(0)
	v_lshlrev_b32_e32 v52, 16, v48
	v_and_b32_e32 v48, 0xffff0000, v48
	v_lshlrev_b32_e32 v53, 16, v49
	v_and_b32_e32 v49, 0xffff0000, v49
	v_lshlrev_b32_e32 v54, 16, v50
	v_and_b32_e32 v50, 0xffff0000, v50
	v_lshlrev_b32_e32 v55, 16, v51
	v_and_b32_e32 v51, 0xffff0000, v51
	v_add_f32_e32 v57, 0, v48
	v_add_f32_e32 v58, 0, v49
	v_add_f32_e32 v59, 0, v50
	v_add_f32_e32 v60, 0, v51
	ds_read_b128 v[48:51], v149 offset:912
	v_add_f32_e32 v52, 0, v52
	v_add_f32_e32 v53, 0, v53
	v_add_f32_e32 v54, 0, v54
	v_add_f32_e32 v55, 0, v55
	s_waitcnt lgkmcnt(0)
	v_lshlrev_b32_e32 v61, 16, v48
	v_and_b32_e32 v48, 0xffff0000, v48
	v_lshlrev_b32_e32 v62, 16, v49
	v_and_b32_e32 v49, 0xffff0000, v49
	v_lshlrev_b32_e32 v63, 16, v50
	v_and_b32_e32 v50, 0xffff0000, v50
	v_lshlrev_b32_e32 v64, 16, v51
	v_and_b32_e32 v51, 0xffff0000, v51
	v_add_f32_e32 v57, v57, v48
	v_add_f32_e32 v58, v58, v49
	v_add_f32_e32 v59, v59, v50
	v_add_f32_e32 v60, v60, v51
	ds_read_b128 v[48:51], v149 offset:1440
	v_add_f32_e32 v52, v52, v61
	v_add_f32_e32 v53, v53, v62
	v_add_f32_e32 v54, v54, v63
	v_add_f32_e32 v55, v55, v64
	s_waitcnt lgkmcnt(0)
	v_lshlrev_b32_e32 v61, 16, v48
	v_and_b32_e32 v48, 0xffff0000, v48
	v_lshlrev_b32_e32 v62, 16, v49
	v_and_b32_e32 v49, 0xffff0000, v49
	v_lshlrev_b32_e32 v63, 16, v50
	v_and_b32_e32 v50, 0xffff0000, v50
	v_lshlrev_b32_e32 v64, 16, v51
	v_and_b32_e32 v51, 0xffff0000, v51
	v_add_f32_e32 v57, v57, v48
	v_add_f32_e32 v58, v58, v49
	v_add_f32_e32 v59, v59, v50
	v_add_f32_e32 v60, v60, v51
	ds_read_b128 v[48:51], v149 offset:1968
	v_add_f32_e32 v52, v52, v61
	v_add_f32_e32 v53, v53, v62
	v_add_f32_e32 v54, v54, v63
	v_add_f32_e32 v55, v55, v64
	s_waitcnt lgkmcnt(0)
	v_lshlrev_b32_e32 v61, 16, v48
	v_and_b32_e32 v48, 0xffff0000, v48
	v_lshlrev_b32_e32 v62, 16, v49
	v_and_b32_e32 v49, 0xffff0000, v49
	v_lshlrev_b32_e32 v63, 16, v50
	v_and_b32_e32 v50, 0xffff0000, v50
	v_lshlrev_b32_e32 v64, 16, v51
	v_and_b32_e32 v51, 0xffff0000, v51
	v_add_f32_e32 v57, v57, v48
	v_add_f32_e32 v58, v58, v49
	v_add_f32_e32 v59, v59, v50
	v_add_f32_e32 v60, v60, v51
	ds_read_b128 v[48:51], v149 offset:2496
	v_add_f32_e32 v52, v52, v61
	v_add_f32_e32 v53, v53, v62
	v_add_f32_e32 v54, v54, v63
	v_add_f32_e32 v55, v55, v64
	s_waitcnt lgkmcnt(0)
	v_lshlrev_b32_e32 v61, 16, v48
	v_and_b32_e32 v48, 0xffff0000, v48
	v_lshlrev_b32_e32 v62, 16, v49
	v_and_b32_e32 v49, 0xffff0000, v49
	v_lshlrev_b32_e32 v63, 16, v50
	v_and_b32_e32 v50, 0xffff0000, v50
	v_lshlrev_b32_e32 v64, 16, v51
	v_and_b32_e32 v51, 0xffff0000, v51
	v_add_f32_e32 v57, v57, v48
	v_add_f32_e32 v58, v58, v49
	v_add_f32_e32 v59, v59, v50
	v_add_f32_e32 v60, v60, v51
	ds_read_b128 v[48:51], v149 offset:3024
	v_add_f32_e32 v52, v52, v61
	v_add_f32_e32 v53, v53, v62
	v_add_f32_e32 v54, v54, v63
	v_add_f32_e32 v55, v55, v64
	s_waitcnt lgkmcnt(0)
	v_lshlrev_b32_e32 v61, 16, v48
	v_and_b32_e32 v48, 0xffff0000, v48
	v_lshlrev_b32_e32 v62, 16, v49
	v_and_b32_e32 v49, 0xffff0000, v49
	v_lshlrev_b32_e32 v63, 16, v50
	v_and_b32_e32 v50, 0xffff0000, v50
	v_lshlrev_b32_e32 v64, 16, v51
	v_and_b32_e32 v51, 0xffff0000, v51
	v_add_f32_e32 v57, v57, v48
	v_add_f32_e32 v58, v58, v49
	v_add_f32_e32 v59, v59, v50
	v_add_f32_e32 v60, v60, v51
	ds_read_b128 v[48:51], v149 offset:3552
	v_add_f32_e32 v52, v52, v61
	v_add_f32_e32 v53, v53, v62
	v_add_f32_e32 v54, v54, v63
	v_add_f32_e32 v55, v55, v64
	s_waitcnt lgkmcnt(0)
	v_lshlrev_b32_e32 v61, 16, v48
	v_and_b32_e32 v48, 0xffff0000, v48
	v_lshlrev_b32_e32 v62, 16, v49
	v_and_b32_e32 v49, 0xffff0000, v49
	v_lshlrev_b32_e32 v63, 16, v50
	v_and_b32_e32 v50, 0xffff0000, v50
	v_lshlrev_b32_e32 v64, 16, v51
	v_and_b32_e32 v51, 0xffff0000, v51
	v_add_f32_e32 v57, v57, v48
	v_add_f32_e32 v58, v58, v49
	v_add_f32_e32 v59, v59, v50
	v_add_f32_e32 v60, v60, v51
	ds_read_b128 v[48:51], v149 offset:4080
	v_add_f32_e32 v52, v52, v61
	v_add_f32_e32 v53, v53, v62
	v_add_f32_e32 v54, v54, v63
	v_add_f32_e32 v55, v55, v64
	s_waitcnt lgkmcnt(0)
	v_lshlrev_b32_e32 v61, 16, v48
	v_lshlrev_b32_e32 v62, 16, v49
	v_lshlrev_b32_e32 v63, 16, v50
	v_lshlrev_b32_e32 v64, 16, v51
	v_add_f32_e32 v61, v52, v61
	v_add_f32_e32 v62, v53, v62
	v_add_f32_e32 v63, v54, v63
	v_add_f32_e32 v64, v55, v64
	ds_read_b128 v[52:55], v149 offset:4608
	v_and_b32_e32 v48, 0xffff0000, v48
	v_and_b32_e32 v49, 0xffff0000, v49
	v_and_b32_e32 v50, 0xffff0000, v50
	v_and_b32_e32 v51, 0xffff0000, v51
	v_add_f32_e32 v57, v57, v48
	v_add_f32_e32 v58, v58, v49
	v_add_f32_e32 v59, v59, v50
	v_add_f32_e32 v60, v60, v51
	s_waitcnt lgkmcnt(0)
	v_lshlrev_b32_e32 v48, 16, v52
	v_and_b32_e32 v49, 0xffff0000, v52
	v_lshlrev_b32_e32 v50, 16, v53
	v_and_b32_e32 v51, 0xffff0000, v53
	v_lshlrev_b32_e32 v52, 16, v54
	v_and_b32_e32 v53, 0xffff0000, v54
	v_lshlrev_b32_e32 v54, 16, v55
	v_and_b32_e32 v55, 0xffff0000, v55
	v_add_f32_e32 v65, v61, v48
	v_add_f32_e32 v66, v58, v51
	v_add_f32_e32 v67, v59, v53
	v_add_f32_e32 v68, v60, v55
	ds_read_b128 v[58:61], v149 offset:5136
	v_add_f32_e32 v57, v57, v49
	v_add_f32_e32 v62, v62, v50
	v_add_f32_e32 v63, v63, v52
	v_add_f32_e32 v64, v64, v54
	s_waitcnt lgkmcnt(0)
	v_lshlrev_b32_e32 v69, 16, v58
	v_and_b32_e32 v58, 0xffff0000, v58
	v_lshlrev_b32_e32 v70, 16, v59
	v_and_b32_e32 v59, 0xffff0000, v59
	v_lshlrev_b32_e32 v71, 16, v60
	v_and_b32_e32 v60, 0xffff0000, v60
	v_lshlrev_b32_e32 v131, 16, v61
	v_and_b32_e32 v61, 0xffff0000, v61
	v_add_f32_e32 v57, v57, v58
	v_add_f32_e32 v66, v66, v59
	v_add_f32_e32 v67, v67, v60
	v_add_f32_e32 v68, v68, v61
	ds_read_b128 v[58:61], v149 offset:5664
	v_add_f32_e32 v65, v65, v69
	v_add_f32_e32 v62, v62, v70
	v_add_f32_e32 v63, v63, v71
	v_add_f32_e32 v64, v64, v131
	s_waitcnt lgkmcnt(0)
	v_lshlrev_b32_e32 v69, 16, v58
	v_and_b32_e32 v58, 0xffff0000, v58
	v_lshlrev_b32_e32 v70, 16, v59
	v_and_b32_e32 v59, 0xffff0000, v59
	v_lshlrev_b32_e32 v71, 16, v60
	v_and_b32_e32 v60, 0xffff0000, v60
	v_lshlrev_b32_e32 v131, 16, v61
	v_and_b32_e32 v61, 0xffff0000, v61
	v_add_f32_e32 v57, v57, v58
	v_add_f32_e32 v66, v66, v59
	v_add_f32_e32 v67, v67, v60
	v_add_f32_e32 v68, v68, v61
	ds_read_b128 v[58:61], v149 offset:6192
	v_add_f32_e32 v65, v65, v69
	v_add_f32_e32 v62, v62, v70
	v_add_f32_e32 v63, v63, v71
	v_add_f32_e32 v64, v64, v131
	s_waitcnt lgkmcnt(0)
	v_lshlrev_b32_e32 v69, 16, v58
	v_and_b32_e32 v58, 0xffff0000, v58
	v_lshlrev_b32_e32 v70, 16, v59
	v_and_b32_e32 v59, 0xffff0000, v59
	v_lshlrev_b32_e32 v71, 16, v60
	v_and_b32_e32 v60, 0xffff0000, v60
	v_lshlrev_b32_e32 v131, 16, v61
	v_and_b32_e32 v61, 0xffff0000, v61
	v_add_f32_e32 v57, v57, v58
	v_add_f32_e32 v66, v66, v59
	v_add_f32_e32 v67, v67, v60
	v_add_f32_e32 v68, v68, v61
	ds_read_b128 v[58:61], v149 offset:6720
	v_add_f32_e32 v65, v65, v69
	v_add_f32_e32 v62, v62, v70
	v_add_f32_e32 v63, v63, v71
	v_add_f32_e32 v64, v64, v131
	s_waitcnt lgkmcnt(0)
	v_lshlrev_b32_e32 v69, 16, v58
	v_and_b32_e32 v58, 0xffff0000, v58
	v_lshlrev_b32_e32 v70, 16, v59
	v_and_b32_e32 v59, 0xffff0000, v59
	v_lshlrev_b32_e32 v71, 16, v60
	v_and_b32_e32 v60, 0xffff0000, v60
	v_lshlrev_b32_e32 v131, 16, v61
	v_and_b32_e32 v61, 0xffff0000, v61
	v_add_f32_e32 v57, v57, v58
	v_add_f32_e32 v66, v66, v59
	v_add_f32_e32 v67, v67, v60
	v_add_f32_e32 v68, v68, v61
	ds_read_b128 v[58:61], v149 offset:7248
	v_add_f32_e32 v65, v65, v69
	v_add_f32_e32 v62, v62, v70
	v_add_f32_e32 v63, v63, v71
	v_add_f32_e32 v64, v64, v131
	s_waitcnt lgkmcnt(0)
	v_lshlrev_b32_e32 v69, 16, v58
	v_and_b32_e32 v58, 0xffff0000, v58
	v_lshlrev_b32_e32 v70, 16, v59
	v_and_b32_e32 v59, 0xffff0000, v59
	v_lshlrev_b32_e32 v71, 16, v60
	v_and_b32_e32 v60, 0xffff0000, v60
	v_lshlrev_b32_e32 v131, 16, v61
	v_and_b32_e32 v61, 0xffff0000, v61
	v_add_f32_e32 v65, v65, v69
	v_add_f32_e32 v69, v57, v58
	v_add_f32_e32 v66, v66, v59
	v_add_f32_e32 v67, v67, v60
	v_add_f32_e32 v68, v68, v61
	ds_read_b128 v[58:61], v149 offset:7776
	v_add_f32_e32 v63, v63, v71
	v_add_f32_e32 v64, v64, v131
	v_add_f32_e32 v62, v62, v70
	s_waitcnt lgkmcnt(0)
	v_lshlrev_b32_e32 v131, 16, v60
	v_lshlrev_b32_e32 v151, 16, v61
	v_and_b32_e32 v152, 0xffff0000, v61
	v_add_f32_e32 v61, v63, v131
	v_add_f32_e32 v63, v64, v151
	v_add_f32_e32 v64, v68, v152
	ds_read_b128 v[152:155], v149 offset:8304
	v_lshlrev_b32_e32 v57, 16, v58
	v_and_b32_e32 v58, 0xffff0000, v58
	v_lshlrev_b32_e32 v70, 16, v59
	v_and_b32_e32 v71, 0xffff0000, v59
	v_and_b32_e32 v133, 0xffff0000, v60
	v_add_f32_e32 v57, v65, v57
	v_add_f32_e32 v58, v69, v58
	v_add_f32_e32 v59, v62, v70
	v_add_f32_e32 v60, v66, v71
	v_add_f32_e32 v62, v67, v133
	s_waitcnt lgkmcnt(0)
	v_lshlrev_b32_e32 v65, 16, v152
	v_and_b32_e32 v66, 0xffff0000, v152
	v_lshlrev_b32_e32 v67, 16, v153
	v_and_b32_e32 v68, 0xffff0000, v153
	v_lshlrev_b32_e32 v69, 16, v154
	v_and_b32_e32 v70, 0xffff0000, v154
	v_lshlrev_b32_e32 v71, 16, v155
	v_and_b32_e32 v131, 0xffff0000, v155
	v_add_f32_e32 v57, v57, v65
	v_add_f32_e32 v58, v58, v66
	v_add_f32_e32 v59, v59, v67
	v_add_f32_e32 v60, v60, v68
	v_add_f32_e32 v61, v61, v69
	v_add_f32_e32 v62, v62, v70
	v_add_f32_e32 v63, v63, v71
	v_add_f32_e32 v64, v64, v131
	v_fma_f32 v48, v56, v57, -v48
	v_fma_f32 v49, v56, v58, -v49
	v_fma_f32 v50, v56, v59, -v50
	v_fma_f32 v51, v56, v60, -v51
	v_fma_f32 v52, v56, v61, -v52
	v_fma_f32 v53, v56, v62, -v53
	v_fma_f32 v54, v56, v63, -v54
	v_fma_f32 v55, v56, v64, -v55
	v_cvt_pk_bf16_f32 v58, v48, v49
	v_cvt_pk_bf16_f32 v59, v50, v51
	v_cvt_pk_bf16_f32 v60, v52, v53
	v_cvt_pk_bf16_f32 v61, v54, v55
	s_waitcnt vmcnt(3)
	v_mfma_f32_16x16x32_bf16 v[48:51], v[90:93], v[58:61], 0
	s_waitcnt vmcnt(2)
	v_mfma_f32_16x16x32_bf16 v[52:55], v[94:97], v[58:61], 0
	s_waitcnt vmcnt(1)
	v_mfma_f32_16x16x32_bf16 v[64:67], v[106:109], v[58:61], 0
	s_waitcnt vmcnt(0)
	v_mfma_f32_16x16x32_bf16 v[68:71], v[110:113], v[58:61], 0
	ds_read_b128 v[58:61], v149 offset:448
	s_waitcnt lgkmcnt(0)
	v_lshlrev_b32_e32 v57, 16, v58
	v_and_b32_e32 v58, 0xffff0000, v58
	v_lshlrev_b32_e32 v62, 16, v59
	v_and_b32_e32 v59, 0xffff0000, v59
	v_lshlrev_b32_e32 v63, 16, v60
	v_and_b32_e32 v60, 0xffff0000, v60
	v_lshlrev_b32_e32 v131, 16, v61
	v_and_b32_e32 v61, 0xffff0000, v61
	v_add_f32_e32 v133, 0, v58
	v_add_f32_e32 v151, 0, v59
	v_add_f32_e32 v152, 0, v60
	v_add_f32_e32 v153, 0, v61
	ds_read_b128 v[58:61], v149 offset:976
	v_add_f32_e32 v57, 0, v57
	v_add_f32_e32 v62, 0, v62
	v_add_f32_e32 v63, 0, v63
	v_add_f32_e32 v131, 0, v131
	s_waitcnt lgkmcnt(0)
	v_lshlrev_b32_e32 v154, 16, v58
	v_and_b32_e32 v58, 0xffff0000, v58
	v_lshlrev_b32_e32 v155, 16, v59
	v_and_b32_e32 v59, 0xffff0000, v59
	v_lshlrev_b32_e32 v156, 16, v60
	v_and_b32_e32 v60, 0xffff0000, v60
	v_lshlrev_b32_e32 v157, 16, v61
	v_and_b32_e32 v61, 0xffff0000, v61
	v_add_f32_e32 v133, v133, v58
	v_add_f32_e32 v151, v151, v59
	v_add_f32_e32 v152, v152, v60
	v_add_f32_e32 v153, v153, v61
	ds_read_b128 v[58:61], v149 offset:1504
	v_add_f32_e32 v57, v57, v154
	v_add_f32_e32 v62, v62, v155
	v_add_f32_e32 v63, v63, v156
	v_add_f32_e32 v131, v131, v157
	s_waitcnt lgkmcnt(0)
	v_lshlrev_b32_e32 v154, 16, v58
	v_and_b32_e32 v58, 0xffff0000, v58
	v_lshlrev_b32_e32 v155, 16, v59
	v_and_b32_e32 v59, 0xffff0000, v59
	v_lshlrev_b32_e32 v156, 16, v60
	v_and_b32_e32 v60, 0xffff0000, v60
	v_lshlrev_b32_e32 v157, 16, v61
	v_and_b32_e32 v61, 0xffff0000, v61
	v_add_f32_e32 v133, v133, v58
	v_add_f32_e32 v151, v151, v59
	v_add_f32_e32 v152, v152, v60
	v_add_f32_e32 v153, v153, v61
	ds_read_b128 v[58:61], v149 offset:2032
	v_add_f32_e32 v57, v57, v154
	v_add_f32_e32 v62, v62, v155
	v_add_f32_e32 v63, v63, v156
	v_add_f32_e32 v131, v131, v157
	s_waitcnt lgkmcnt(0)
	v_lshlrev_b32_e32 v154, 16, v58
	v_and_b32_e32 v58, 0xffff0000, v58
	v_lshlrev_b32_e32 v155, 16, v59
	v_and_b32_e32 v59, 0xffff0000, v59
	v_lshlrev_b32_e32 v156, 16, v60
	v_and_b32_e32 v60, 0xffff0000, v60
	v_lshlrev_b32_e32 v157, 16, v61
	v_and_b32_e32 v61, 0xffff0000, v61
	v_add_f32_e32 v133, v133, v58
	v_add_f32_e32 v151, v151, v59
	v_add_f32_e32 v152, v152, v60
	v_add_f32_e32 v153, v153, v61
	ds_read_b128 v[58:61], v149 offset:2560
	v_add_f32_e32 v57, v57, v154
	v_add_f32_e32 v62, v62, v155
	v_add_f32_e32 v63, v63, v156
	v_add_f32_e32 v131, v131, v157
	s_waitcnt lgkmcnt(0)
	v_lshlrev_b32_e32 v154, 16, v58
	v_and_b32_e32 v58, 0xffff0000, v58
	v_lshlrev_b32_e32 v155, 16, v59
	v_and_b32_e32 v59, 0xffff0000, v59
	v_lshlrev_b32_e32 v156, 16, v60
	v_and_b32_e32 v60, 0xffff0000, v60
	v_lshlrev_b32_e32 v157, 16, v61
	v_and_b32_e32 v61, 0xffff0000, v61
	v_add_f32_e32 v133, v133, v58
	v_add_f32_e32 v151, v151, v59
	v_add_f32_e32 v152, v152, v60
	v_add_f32_e32 v153, v153, v61
	ds_read_b128 v[58:61], v149 offset:3088
	v_add_f32_e32 v57, v57, v154
	v_add_f32_e32 v62, v62, v155
	v_add_f32_e32 v63, v63, v156
	v_add_f32_e32 v131, v131, v157
	s_waitcnt lgkmcnt(0)
	v_lshlrev_b32_e32 v154, 16, v58
	v_and_b32_e32 v58, 0xffff0000, v58
	v_lshlrev_b32_e32 v155, 16, v59
	v_and_b32_e32 v59, 0xffff0000, v59
	v_lshlrev_b32_e32 v156, 16, v60
	v_and_b32_e32 v60, 0xffff0000, v60
	v_lshlrev_b32_e32 v157, 16, v61
	v_and_b32_e32 v61, 0xffff0000, v61
	v_add_f32_e32 v133, v133, v58
	v_add_f32_e32 v151, v151, v59
	v_add_f32_e32 v152, v152, v60
	v_add_f32_e32 v153, v153, v61
	ds_read_b128 v[58:61], v149 offset:3616
	v_add_f32_e32 v57, v57, v154
	v_add_f32_e32 v62, v62, v155
	v_add_f32_e32 v63, v63, v156
	v_add_f32_e32 v131, v131, v157
	s_waitcnt lgkmcnt(0)
	v_lshlrev_b32_e32 v154, 16, v58
	v_and_b32_e32 v58, 0xffff0000, v58
	v_lshlrev_b32_e32 v155, 16, v59
	v_and_b32_e32 v59, 0xffff0000, v59
	v_lshlrev_b32_e32 v156, 16, v60
	v_and_b32_e32 v60, 0xffff0000, v60
	v_lshlrev_b32_e32 v157, 16, v61
	v_and_b32_e32 v61, 0xffff0000, v61
	v_add_f32_e32 v133, v133, v58
	v_add_f32_e32 v151, v151, v59
	v_add_f32_e32 v152, v152, v60
	v_add_f32_e32 v153, v153, v61
	ds_read_b128 v[58:61], v149 offset:4144
	v_add_f32_e32 v57, v57, v154
	v_add_f32_e32 v62, v62, v155
	v_add_f32_e32 v63, v63, v156
	v_add_f32_e32 v131, v131, v157
	s_waitcnt lgkmcnt(0)
	v_lshlrev_b32_e32 v154, 16, v58
	v_lshlrev_b32_e32 v155, 16, v59
	v_lshlrev_b32_e32 v156, 16, v60
	v_and_b32_e32 v60, 0xffff0000, v60
	v_lshlrev_b32_e32 v157, 16, v61
	v_and_b32_e32 v61, 0xffff0000, v61
	v_add_f32_e32 v158, v57, v154
	v_add_f32_e32 v159, v62, v155
	v_add_f32_e32 v160, v152, v60
	v_add_f32_e32 v161, v153, v61
	ds_read_b128 v[152:155], v149 offset:4672
	v_and_b32_e32 v58, 0xffff0000, v58
	v_and_b32_e32 v59, 0xffff0000, v59
	v_add_f32_e32 v133, v133, v58
	v_add_f32_e32 v151, v151, v59
	v_add_f32_e32 v156, v63, v156
	v_add_f32_e32 v157, v131, v157
	s_waitcnt lgkmcnt(0)
	v_lshlrev_b32_e32 v57, 16, v152
	v_and_b32_e32 v58, 0xffff0000, v152
	v_lshlrev_b32_e32 v59, 16, v153
	v_and_b32_e32 v60, 0xffff0000, v153
	v_lshlrev_b32_e32 v61, 16, v154
	v_and_b32_e32 v62, 0xffff0000, v154
	v_lshlrev_b32_e32 v63, 16, v155
	v_and_b32_e32 v131, 0xffff0000, v155
	ds_read_b128 v[152:155], v149 offset:5200
	v_add_f32_e32 v133, v133, v58
	v_add_f32_e32 v151, v151, v60
	v_add_f32_e32 v160, v160, v62
	v_add_f32_e32 v161, v161, v131
	s_waitcnt lgkmcnt(0)
	v_lshlrev_b32_e32 v162, 16, v152
	v_and_b32_e32 v152, 0xffff0000, v152
	v_lshlrev_b32_e32 v163, 16, v153
	v_and_b32_e32 v153, 0xffff0000, v153
	v_lshlrev_b32_e32 v164, 16, v154
	v_and_b32_e32 v154, 0xffff0000, v154
	v_lshlrev_b32_e32 v165, 16, v155
	v_and_b32_e32 v155, 0xffff0000, v155
	v_add_f32_e32 v133, v133, v152
	v_add_f32_e32 v151, v151, v153
	v_add_f32_e32 v160, v160, v154
	v_add_f32_e32 v161, v161, v155
	ds_read_b128 v[152:155], v149 offset:5728
	v_add_f32_e32 v158, v158, v57
	v_add_f32_e32 v159, v159, v59
	v_add_f32_e32 v156, v156, v61
	v_add_f32_e32 v157, v157, v63
	v_add_f32_e32 v158, v158, v162
	v_add_f32_e32 v159, v159, v163
	v_add_f32_e32 v156, v156, v164
	v_add_f32_e32 v157, v157, v165
	s_waitcnt lgkmcnt(0)
	v_lshlrev_b32_e32 v162, 16, v152
	v_and_b32_e32 v152, 0xffff0000, v152
	v_lshlrev_b32_e32 v163, 16, v153
	v_and_b32_e32 v153, 0xffff0000, v153
	v_lshlrev_b32_e32 v164, 16, v154
	v_and_b32_e32 v154, 0xffff0000, v154
	v_lshlrev_b32_e32 v165, 16, v155
	v_and_b32_e32 v155, 0xffff0000, v155
	v_add_f32_e32 v133, v133, v152
	v_add_f32_e32 v151, v151, v153
	v_add_f32_e32 v160, v160, v154
	v_add_f32_e32 v161, v161, v155
	ds_read_b128 v[152:155], v149 offset:6256
	v_add_f32_e32 v158, v158, v162
	v_add_f32_e32 v159, v159, v163
	v_add_f32_e32 v156, v156, v164
	v_add_f32_e32 v157, v157, v165
	s_waitcnt lgkmcnt(0)
	v_lshlrev_b32_e32 v162, 16, v152
	v_and_b32_e32 v152, 0xffff0000, v152
	v_lshlrev_b32_e32 v163, 16, v153
	v_and_b32_e32 v153, 0xffff0000, v153
	v_lshlrev_b32_e32 v164, 16, v154
	v_and_b32_e32 v154, 0xffff0000, v154
	v_lshlrev_b32_e32 v165, 16, v155
	v_and_b32_e32 v155, 0xffff0000, v155
	v_add_f32_e32 v133, v133, v152
	v_add_f32_e32 v151, v151, v153
	v_add_f32_e32 v160, v160, v154
	v_add_f32_e32 v161, v161, v155
	ds_read_b128 v[152:155], v149 offset:6784
	v_add_f32_e32 v158, v158, v162
	v_add_f32_e32 v159, v159, v163
	v_add_f32_e32 v156, v156, v164
	v_add_f32_e32 v157, v157, v165
	s_waitcnt lgkmcnt(0)
	v_lshlrev_b32_e32 v162, 16, v152
	v_and_b32_e32 v152, 0xffff0000, v152
	v_lshlrev_b32_e32 v163, 16, v153
	v_and_b32_e32 v153, 0xffff0000, v153
	v_lshlrev_b32_e32 v164, 16, v154
	v_and_b32_e32 v154, 0xffff0000, v154
	v_lshlrev_b32_e32 v165, 16, v155
	v_and_b32_e32 v155, 0xffff0000, v155
	v_add_f32_e32 v133, v133, v152
	v_add_f32_e32 v151, v151, v153
	v_add_f32_e32 v160, v160, v154
	v_add_f32_e32 v161, v161, v155
	ds_read_b128 v[152:155], v149 offset:7312
	v_add_f32_e32 v158, v158, v162
	v_add_f32_e32 v159, v159, v163
	v_add_f32_e32 v156, v156, v164
	v_add_f32_e32 v157, v157, v165
	s_waitcnt lgkmcnt(0)
	v_lshlrev_b32_e32 v162, 16, v152
	v_and_b32_e32 v152, 0xffff0000, v152
	v_lshlrev_b32_e32 v163, 16, v153
	v_and_b32_e32 v153, 0xffff0000, v153
	v_lshlrev_b32_e32 v164, 16, v154
	v_and_b32_e32 v154, 0xffff0000, v154
	v_lshlrev_b32_e32 v165, 16, v155
	v_and_b32_e32 v155, 0xffff0000, v155
	v_add_f32_e32 v133, v133, v152
	v_add_f32_e32 v151, v151, v153
	v_add_f32_e32 v160, v160, v154
	v_add_f32_e32 v161, v161, v155
	ds_read_b128 v[152:155], v149 offset:7840
	v_add_f32_e32 v158, v158, v162
	v_add_f32_e32 v159, v159, v163
	v_add_f32_e32 v156, v156, v164
	v_add_f32_e32 v157, v157, v165
	s_waitcnt lgkmcnt(0)
	v_lshlrev_b32_e32 v162, 16, v152
	v_and_b32_e32 v152, 0xffff0000, v152
	v_lshlrev_b32_e32 v163, 16, v153
	v_and_b32_e32 v153, 0xffff0000, v153
	v_lshlrev_b32_e32 v164, 16, v154
	v_and_b32_e32 v154, 0xffff0000, v154
	v_lshlrev_b32_e32 v165, 16, v155
	v_and_b32_e32 v155, 0xffff0000, v155
	v_add_f32_e32 v133, v133, v152
	v_add_f32_e32 v151, v151, v153
	v_add_f32_e32 v160, v160, v154
	v_add_f32_e32 v161, v161, v155
	ds_read_b128 v[152:155], v149 offset:8368
	v_add_f32_e32 v158, v158, v162
	v_add_f32_e32 v159, v159, v163
	v_add_f32_e32 v156, v156, v164
	v_add_f32_e32 v157, v157, v165
	s_waitcnt lgkmcnt(0)
	v_lshlrev_b32_e32 v162, 16, v152
	v_and_b32_e32 v152, 0xffff0000, v152
	v_lshlrev_b32_e32 v163, 16, v153
	v_and_b32_e32 v153, 0xffff0000, v153
	v_lshlrev_b32_e32 v164, 16, v154
	v_and_b32_e32 v154, 0xffff0000, v154
	v_lshlrev_b32_e32 v165, 16, v155
	v_and_b32_e32 v155, 0xffff0000, v155
	v_add_f32_e32 v158, v158, v162
	v_add_f32_e32 v133, v133, v152
	v_add_f32_e32 v152, v159, v163
	v_add_f32_e32 v151, v151, v153
	v_add_f32_e32 v153, v156, v164
	v_add_f32_e32 v154, v160, v154
	v_add_f32_e32 v156, v157, v165
	v_add_f32_e32 v155, v161, v155
	v_fma_f32 v57, v56, v158, -v57
	v_fma_f32 v58, v56, v133, -v58
	v_fma_f32 v59, v56, v152, -v59
	v_fma_f32 v60, v56, v151, -v60
	v_fma_f32 v61, v56, v153, -v61
	v_fma_f32 v62, v56, v154, -v62
	v_fma_f32 v63, v56, v156, -v63
	v_fma_f32 v56, v56, v155, -v131
	v_cvt_pk_bf16_f32 v152, v57, v58
	v_cvt_pk_bf16_f32 v153, v59, v60
	v_cvt_pk_bf16_f32 v154, v61, v62
	v_cvt_pk_bf16_f32 v155, v63, v56
	s_waitcnt vmcnt(0)
	v_mfma_f32_16x16x32_bf16 v[60:63], v[222:225], v[152:155], v[48:51]
	s_nop 2
	v_mov_b32_e32 v133, v209
	s_waitcnt vmcnt(0)
	v_mfma_f32_16x16x32_bf16 v[56:59], v[226:229], v[152:155], v[52:55]
	s_waitcnt vmcnt(0)
	v_mfma_f32_16x16x32_bf16 v[52:55], v[230:233], v[152:155], v[64:67]
	s_nop 1
	v_pk_mul_f32 v[64:65], v[14:15], v[14:15]
	v_pk_mul_f32 v[66:67], v[12:13], v[12:13]
	s_waitcnt vmcnt(0)
	v_mfma_f32_16x16x32_bf16 v[48:51], v[234:237], v[152:155], v[68:71]
	s_nop 2
	v_pk_mov_b32 v[68:69], v[66:67], v[64:65] op_sel:[1,0]
	v_mov_b32_e32 v67, v65
	v_pk_add_f32 v[64:65], v[68:69], v[66:67]
	v_pk_mul_f32 v[66:67], v[10:11], v[10:11]
	v_pk_mul_f32 v[68:69], v[8:9], v[8:9]
	v_pk_add_f32 v[64:65], v[64:65], v[64:65] op_sel:[0,1] op_sel_hi:[1,0]
	v_pk_mov_b32 v[70:71], v[68:69], v[66:67] op_sel:[1,0]
	v_mov_b32_e32 v69, v67
	v_pk_add_f32 v[66:67], v[70:71], v[68:69]
	v_mul_f32_e32 v68, v0, v0
	v_mul_f32_e32 v69, v1, v1
	v_pk_add_f32 v[66:67], v[66:67], v[66:67] op_sel:[0,1] op_sel_hi:[1,0]
	v_mov_b32_e32 v65, v68
	v_mov_b32_e32 v67, v69
	v_pk_add_f32 v[64:65], v[64:65], v[66:67]
	v_mul_f32_e32 v66, v5, v5
	v_mul_f32_e32 v68, v7, v7
	v_mul_f32_e32 v70, v2, v2
	v_mul_f32_e32 v71, v3, v3
	v_pk_fma_f32 v[66:67], v[4:5], v[4:5], v[66:67] op_sel_hi:[1,1,0]
	v_pk_fma_f32 v[68:69], v[6:7], v[6:7], v[68:69] op_sel_hi:[1,1,0]
	v_mov_b32_e32 v67, v70
	v_mov_b32_e32 v69, v71
	v_pk_add_f32 v[66:67], v[66:67], v[68:69]
	v_pk_mul_f32 v[68:69], v[28:29], v[28:29]
	v_pk_add_f32 v[64:65], v[64:65], v[66:67]
	v_pk_mul_f32 v[66:67], v[30:31], v[30:31]
	v_pk_add_f32 v[64:65], v[64:65], v[64:65] op_sel:[0,1] op_sel_hi:[1,0]
	v_pk_mov_b32 v[70:71], v[68:69], v[66:67] op_sel:[1,0]
	v_mov_b32_e32 v69, v67
	v_pk_add_f32 v[66:67], v[70:71], v[68:69]
	v_mul_f32_e32 v68, v20, v20
	v_mul_f32_e32 v69, v21, v21
	v_pk_add_f32 v[66:67], v[66:67], v[66:67] op_sel:[0,1] op_sel_hi:[1,0]
	v_mov_b32_e32 v65, v68
	v_mov_b32_e32 v67, v69
	v_pk_add_f32 v[64:65], v[64:65], v[66:67]
	v_mul_f32_e32 v66, v25, v25
	v_mul_f32_e32 v68, v27, v27
	v_mul_f32_e32 v70, v22, v22
	v_mul_f32_e32 v71, v23, v23
	v_pk_fma_f32 v[66:67], v[24:25], v[24:25], v[66:67] op_sel_hi:[1,1,0]
	v_pk_fma_f32 v[68:69], v[26:27], v[26:27], v[68:69] op_sel_hi:[1,1,0]
	v_mov_b32_e32 v67, v70
	v_mov_b32_e32 v69, v71
	v_pk_add_f32 v[66:67], v[66:67], v[68:69]
	v_pk_mul_f32 v[68:69], v[16:17], v[16:17]
	v_pk_add_f32 v[64:65], v[64:65], v[66:67]
	v_pk_mul_f32 v[66:67], v[18:19], v[18:19]
	v_pk_add_f32 v[64:65], v[64:65], v[64:65] op_sel:[0,1] op_sel_hi:[1,0]
	v_pk_mov_b32 v[70:71], v[68:69], v[66:67] op_sel:[1,0]
	v_mov_b32_e32 v69, v67
	v_pk_add_f32 v[66:67], v[70:71], v[68:69]
	v_mul_f32_e32 v68, v40, v40
	v_mul_f32_e32 v69, v41, v41
	v_pk_add_f32 v[66:67], v[66:67], v[66:67] op_sel:[0,1] op_sel_hi:[1,0]
	v_mov_b32_e32 v65, v68
	v_mov_b32_e32 v67, v69
	v_pk_add_f32 v[64:65], v[64:65], v[66:67]
	v_mul_f32_e32 v66, v45, v45
	v_mul_f32_e32 v68, v47, v47
	v_mul_f32_e32 v70, v42, v42
	v_mul_f32_e32 v71, v43, v43
	v_pk_fma_f32 v[66:67], v[44:45], v[44:45], v[66:67] op_sel_hi:[1,1,0]
	v_pk_fma_f32 v[68:69], v[46:47], v[46:47], v[68:69] op_sel_hi:[1,1,0]
	v_mov_b32_e32 v67, v70
	v_mov_b32_e32 v69, v71
	v_pk_add_f32 v[66:67], v[66:67], v[68:69]
	v_pk_mul_f32 v[68:69], v[36:37], v[36:37]
	v_pk_add_f32 v[64:65], v[64:65], v[66:67]
	v_pk_mul_f32 v[66:67], v[38:39], v[38:39]
	v_pk_add_f32 v[64:65], v[64:65], v[64:65] op_sel:[0,1] op_sel_hi:[1,0]
	v_pk_mov_b32 v[70:71], v[68:69], v[66:67] op_sel:[1,0]
	v_mov_b32_e32 v69, v67
	v_pk_add_f32 v[66:67], v[70:71], v[68:69]
	v_mul_f32_e32 v68, v60, v60
	v_mul_f32_e32 v69, v61, v61
	v_pk_add_f32 v[66:67], v[66:67], v[66:67] op_sel:[0,1] op_sel_hi:[1,0]
	v_mov_b32_e32 v65, v68
	v_mov_b32_e32 v67, v69
	v_pk_add_f32 v[64:65], v[64:65], v[66:67]
	v_mul_f32_e32 v66, v33, v33
	v_mul_f32_e32 v68, v35, v35
	v_mul_f32_e32 v70, v62, v62
	v_mul_f32_e32 v71, v63, v63
	v_pk_fma_f32 v[66:67], v[32:33], v[32:33], v[66:67] op_sel_hi:[1,1,0]
	v_pk_fma_f32 v[68:69], v[34:35], v[34:35], v[68:69] op_sel_hi:[1,1,0]
	v_mov_b32_e32 v67, v70
	v_mov_b32_e32 v69, v71
	v_pk_add_f32 v[66:67], v[66:67], v[68:69]
	v_pk_mul_f32 v[68:69], v[56:57], v[56:57]
	v_pk_add_f32 v[64:65], v[64:65], v[66:67]
	v_pk_mul_f32 v[66:67], v[58:59], v[58:59]
	v_pk_add_f32 v[64:65], v[64:65], v[64:65] op_sel:[0,1] op_sel_hi:[1,0]
	v_pk_mov_b32 v[70:71], v[68:69], v[66:67] op_sel:[1,0]
	v_mov_b32_e32 v69, v67
	v_pk_add_f32 v[66:67], v[70:71], v[68:69]
	v_mul_f32_e32 v68, v48, v48
	v_mul_f32_e32 v69, v49, v49
	v_pk_add_f32 v[66:67], v[66:67], v[66:67] op_sel:[0,1] op_sel_hi:[1,0]
	v_mov_b32_e32 v65, v68
	v_mov_b32_e32 v67, v69
	v_pk_add_f32 v[64:65], v[64:65], v[66:67]
	v_mul_f32_e32 v66, v53, v53
	v_mul_f32_e32 v68, v55, v55
	v_mul_f32_e32 v70, v50, v50
	v_mul_f32_e32 v71, v51, v51
	v_pk_fma_f32 v[66:67], v[52:53], v[52:53], v[66:67] op_sel_hi:[1,1,0]
	v_pk_fma_f32 v[68:69], v[54:55], v[54:55], v[68:69] op_sel_hi:[1,1,0]
	v_mov_b32_e32 v67, v70
	v_mov_b32_e32 v69, v71
	v_pk_add_f32 v[66:67], v[66:67], v[68:69]
	v_and_b32_e32 v68, 64, v245
	v_pk_add_f32 v[64:65], v[64:65], v[66:67]
	v_xor_b32_e32 v67, 16, v245
	v_add_u32_e32 v68, 64, v68
	v_cmp_lt_i32_e32 vcc, v67, v68
	v_add_f32_e32 v66, v64, v65
	v_lshl_add_u64 v[64:65], s[84:85], 0, v[134:135]
	v_cndmask_b32_e32 v67, v245, v67, vcc
	v_lshlrev_b32_e32 v67, 2, v67
	ds_bpermute_b32 v67, v67, v66
	v_lshl_add_u64 v[64:65], v[64:65], 0, v[132:133]
	s_waitcnt lgkmcnt(0)
	v_add_f32_e32 v66, v66, v67
	v_xor_b32_e32 v67, 32, v245
	v_cmp_lt_i32_e32 vcc, v67, v68
	v_lshl_add_u64 v[68:69], v[64:65], 0, s[18:19]
	s_nop 0
	v_cndmask_b32_e32 v67, v245, v67, vcc
	v_lshlrev_b32_e32 v67, 2, v67
	ds_bpermute_b32 v67, v67, v66
	s_waitcnt lgkmcnt(0)
	v_add_f32_e32 v66, v66, v67
	v_fmamk_f32 v66, v66, 0x3b800000, v244
	v_cmp_gt_f32_e32 vcc, s7, v66
	v_mul_f32_e32 v67, 0x4b800000, v66
	s_nop 0
	v_cndmask_b32_e32 v66, v66, v67, vcc
	v_rsq_f32_e32 v66, v66
	s_nop 0
	v_mul_f32_e32 v67, 0x45800000, v66
	v_cndmask_b32_e32 v66, v66, v67, vcc
	v_mbcnt_lo_u32_b32 v78, -1, 0
	v_mbcnt_hi_u32_b32 v78, -1, v78
	v_lshrrev_b32_e32 v78, 4, v78
	v_and_b32_e32 v78, 1, v78
	v_mul_u32_u24_e32 v78, 24, v78
	v_mov_b32_e32 v79, v209
	v_lshl_add_u64 v[80:81], v[68:69], 0, v[78:79]
	v_mul_f32_e32 v12, v12, v66
	v_mul_f32_e32 v13, v13, v66
	v_cvt_pk_bf16_f32 v122, v12, v13
	v_mul_f32_e32 v14, v14, v66
	v_mul_f32_e32 v15, v15, v66
	v_cvt_pk_bf16_f32 v123, v14, v15
	v_mul_f32_e32 v8, v8, v66
	v_mul_f32_e32 v9, v9, v66
	v_cvt_pk_bf16_f32 v124, v8, v9
	v_mul_f32_e32 v10, v10, v66
	v_mul_f32_e32 v11, v11, v66
	v_cvt_pk_bf16_f32 v125, v10, v11
	s_nop 1
	v_permlane16_swap_b32_e32 v122, v124
	v_permlane16_swap_b32_e32 v123, v125
	global_store_dwordx4 v[80:81], v[122:125], off
	v_mul_f32_e32 v4, v4, v66
	v_mul_f32_e32 v5, v5, v66
	v_cvt_pk_bf16_f32 v126, v4, v5
	v_mul_f32_e32 v6, v6, v66
	v_mul_f32_e32 v7, v7, v66
	v_cvt_pk_bf16_f32 v127, v6, v7
	v_mul_f32_e32 v0, v0, v66
	v_mul_f32_e32 v1, v1, v66
	v_cvt_pk_bf16_f32 v128, v0, v1
	v_mul_f32_e32 v2, v2, v66
	v_mul_f32_e32 v3, v3, v66
	v_cvt_pk_bf16_f32 v129, v2, v3
	s_nop 1
	v_permlane16_swap_b32_e32 v126, v128
	v_permlane16_swap_b32_e32 v127, v129
	global_store_dwordx4 v[80:81], v[126:129], off offset:64
	v_mul_f32_e32 v28, v28, v66
	v_mul_f32_e32 v29, v29, v66
	v_cvt_pk_bf16_f32 v122, v28, v29
	v_mul_f32_e32 v30, v30, v66
	v_mul_f32_e32 v31, v31, v66
	v_cvt_pk_bf16_f32 v123, v30, v31
	v_mul_f32_e32 v24, v24, v66
	v_mul_f32_e32 v25, v25, v66
	v_cvt_pk_bf16_f32 v124, v24, v25
	v_mul_f32_e32 v26, v26, v66
	v_mul_f32_e32 v27, v27, v66
	v_cvt_pk_bf16_f32 v125, v26, v27
	s_nop 1
	v_permlane16_swap_b32_e32 v122, v124
	v_permlane16_swap_b32_e32 v123, v125
	global_store_dwordx4 v[80:81], v[122:125], off offset:128
	v_mul_f32_e32 v20, v20, v66
	v_mul_f32_e32 v21, v21, v66
	v_cvt_pk_bf16_f32 v126, v20, v21
	v_mul_f32_e32 v22, v22, v66
	v_mul_f32_e32 v23, v23, v66
	v_cvt_pk_bf16_f32 v127, v22, v23
	v_mul_f32_e32 v16, v16, v66
	v_mul_f32_e32 v17, v17, v66
	v_cvt_pk_bf16_f32 v128, v16, v17
	v_mul_f32_e32 v18, v18, v66
	v_mul_f32_e32 v19, v19, v66
	v_cvt_pk_bf16_f32 v129, v18, v19
	s_nop 1
	v_permlane16_swap_b32_e32 v126, v128
	v_permlane16_swap_b32_e32 v127, v129
	global_store_dwordx4 v[80:81], v[126:129], off offset:192
	v_mul_f32_e32 v44, v44, v66
	v_mul_f32_e32 v45, v45, v66
	v_cvt_pk_bf16_f32 v122, v44, v45
	v_mul_f32_e32 v46, v46, v66
	v_mul_f32_e32 v47, v47, v66
	v_cvt_pk_bf16_f32 v123, v46, v47
	v_mul_f32_e32 v40, v40, v66
	v_mul_f32_e32 v41, v41, v66
	v_cvt_pk_bf16_f32 v124, v40, v41
	v_mul_f32_e32 v42, v42, v66
	v_mul_f32_e32 v43, v43, v66
	v_cvt_pk_bf16_f32 v125, v42, v43
	s_nop 1
	v_permlane16_swap_b32_e32 v122, v124
	v_permlane16_swap_b32_e32 v123, v125
	global_store_dwordx4 v[80:81], v[122:125], off offset:256
	v_mul_f32_e32 v36, v36, v66
	v_mul_f32_e32 v37, v37, v66
	v_cvt_pk_bf16_f32 v126, v36, v37
	v_mul_f32_e32 v38, v38, v66
	v_mul_f32_e32 v39, v39, v66
	v_cvt_pk_bf16_f32 v127, v38, v39
	v_mul_f32_e32 v32, v32, v66
	v_mul_f32_e32 v33, v33, v66
	v_cvt_pk_bf16_f32 v128, v32, v33
	v_mul_f32_e32 v34, v34, v66
	v_mul_f32_e32 v35, v35, v66
	v_cvt_pk_bf16_f32 v129, v34, v35
	s_nop 1
	v_permlane16_swap_b32_e32 v126, v128
	v_permlane16_swap_b32_e32 v127, v129
	global_store_dwordx4 v[80:81], v[126:129], off offset:320
	v_mul_f32_e32 v60, v60, v66
	v_mul_f32_e32 v61, v61, v66
	v_cvt_pk_bf16_f32 v122, v60, v61
	v_mul_f32_e32 v62, v62, v66
	v_mul_f32_e32 v63, v63, v66
	v_cvt_pk_bf16_f32 v123, v62, v63
	v_mul_f32_e32 v56, v56, v66
	v_mul_f32_e32 v57, v57, v66
	v_cvt_pk_bf16_f32 v124, v56, v57
	v_mul_f32_e32 v58, v58, v66
	v_mul_f32_e32 v59, v59, v66
	v_cvt_pk_bf16_f32 v125, v58, v59
	s_nop 1
	v_permlane16_swap_b32_e32 v122, v124
	v_permlane16_swap_b32_e32 v123, v125
	global_store_dwordx4 v[80:81], v[122:125], off offset:384
	v_mul_f32_e32 v52, v52, v66
	v_mul_f32_e32 v53, v53, v66
	v_cvt_pk_bf16_f32 v126, v52, v53
	v_mul_f32_e32 v54, v54, v66
	v_mul_f32_e32 v55, v55, v66
	v_cvt_pk_bf16_f32 v127, v54, v55
	v_mul_f32_e32 v48, v48, v66
	v_mul_f32_e32 v49, v49, v66
	v_cvt_pk_bf16_f32 v128, v48, v49
	v_mul_f32_e32 v50, v50, v66
	v_mul_f32_e32 v51, v51, v66
	v_cvt_pk_bf16_f32 v129, v50, v51
	s_nop 1
	v_permlane16_swap_b32_e32 v126, v128
	v_permlane16_swap_b32_e32 v127, v129
	global_store_dwordx4 v[80:81], v[126:129], off offset:448
	s_waitcnt lgkmcnt(0)
	s_cbranch_scc1 .LBB0_235
	v_readlane_b32 s16, v253, 49
	s_mov_b64 s[36:37], 0xc000800

.LBB0_239:
	v_lshlrev_b64 v[32:33], 11, v[32:33]
	v_lshl_add_u64 v[112:113], s[84:85], 0, v[32:33]
	ds_read_b128 v[36:39], v133
	ds_read_b128 v[80:83], v133 offset:47872
	ds_read_b128 v[40:43], v133 offset:4352
	ds_read_b128 v[52:55], v133 offset:64
	ds_read_b128 v[44:47], v133 offset:8704
	ds_read_b128 v[48:51], v133 offset:13056
	ds_read_b128 v[72:75], v133 offset:39168
	ds_read_b128 v[76:79], v133 offset:43520
	s_mov_b64 s[18:19], 0x1a000600
	s_add_i32 s9, s9, s3
	s_add_i32 s20, s20, s0
	s_add_i32 s2, s2, s3
	s_cmpk_lt_i32 s9, 0x200
	s_waitcnt lgkmcnt(7)
	v_mfma_f32_16x16x32_bf16 v[36:39], v[36:39], v[164:167], 0
	ds_read_b128 v[60:63], v133 offset:26112
	ds_read_b128 v[68:71], v133 offset:17472
	s_waitcnt lgkmcnt(7)
	v_mfma_f32_16x16x32_bf16 v[40:43], v[40:43], v[164:167], 0
	ds_read_b128 v[64:67], v133 offset:30464
	ds_read_b128 v[56:59], v133 offset:21760
	ds_read_b128 v[84:87], v133 offset:34880
	s_waitcnt lgkmcnt(8)
	v_mfma_f32_16x16x32_bf16 v[44:47], v[44:47], v[164:167], 0
	ds_read_b128 v[154:157], v133 offset:65280
	ds_read_b128 v[158:161], v133 offset:52288
	ds_read_b128 v[92:95], v133 offset:60928
	s_waitcnt lgkmcnt(10)
	v_mfma_f32_16x16x32_bf16 v[32:35], v[48:51], v[164:167], 0
	v_mfma_f32_16x16x32_bf16 v[36:39], v[52:55], v[172:175], v[36:39]
	ds_read_b128 v[100:103], v133 offset:4416
	ds_read_b128 v[104:107], v133 offset:8768
	ds_read_b128 v[246:249], v133 offset:13120
	s_waitcnt lgkmcnt(2)
	v_mfma_f32_16x16x32_bf16 v[40:43], v[100:103], v[172:175], v[40:43]
	ds_read_b128 v[100:103], v133 offset:128
	s_waitcnt lgkmcnt(2)
	v_mfma_f32_16x16x32_bf16 v[44:47], v[104:107], v[172:175], v[44:47]
	ds_read_b128 v[104:107], v133 offset:4480
	s_waitcnt lgkmcnt(2)
	v_mfma_f32_16x16x32_bf16 v[32:35], v[246:249], v[172:175], v[32:35]
	ds_read_b128 v[246:249], v133 offset:8832
	s_waitcnt lgkmcnt(2)
	v_mfma_f32_16x16x32_bf16 v[36:39], v[100:103], v[176:179], v[36:39]
	ds_read_b128 v[100:103], v133 offset:13184
	s_waitcnt lgkmcnt(2)
	v_mfma_f32_16x16x32_bf16 v[40:43], v[104:107], v[176:179], v[40:43]
	ds_read_b128 v[104:107], v133 offset:192
	s_waitcnt lgkmcnt(2)
	v_mfma_f32_16x16x32_bf16 v[52:55], v[246:249], v[176:179], v[44:47]
	ds_read_b128 v[246:249], v133 offset:4544
	s_nop 2
	s_waitcnt lgkmcnt(2)
	v_mfma_f32_16x16x32_bf16 v[32:35], v[100:103], v[176:179], v[32:35]
	ds_read_b128 v[100:103], v133 offset:8896
	s_waitcnt lgkmcnt(2)
	v_mfma_f32_16x16x32_bf16 v[44:47], v[104:107], v[180:183], v[36:39]
	ds_read_b128 v[104:107], v133 offset:13248
	s_nop 2
	s_nop 3
	v_pk_add_f32 v[44:45], v[234:235], v[44:45] op_sel_hi:[0,1]
	s_waitcnt lgkmcnt(2)
	v_mfma_f32_16x16x32_bf16 v[40:43], v[246:249], v[180:183], v[40:43]
	ds_read_b128 v[246:249], v133 offset:17408
	v_pk_add_f32 v[46:47], v[234:235], v[46:47] op_sel_hi:[0,1]
	s_nop 5
	v_pk_add_f32 v[42:43], v[234:235], v[42:43] op_sel_hi:[0,1]
	s_waitcnt lgkmcnt(2)
	v_mfma_f32_16x16x32_bf16 v[36:39], v[100:103], v[180:183], v[52:55]
	ds_read_b128 v[100:103], v133 offset:21824
	s_nop 2
	v_pk_add_f32 v[40:41], v[234:235], v[40:41] op_sel_hi:[0,1]
	s_nop 2
	v_add_f32_e32 v37, v234, v37
	s_waitcnt lgkmcnt(2)
	v_mfma_f32_16x16x32_bf16 v[32:35], v[104:107], v[180:183], v[32:35]
	ds_read_b128 v[104:107], v133 offset:26176
	v_add_f32_e32 v38, v234, v38
	s_waitcnt lgkmcnt(2)
	v_mfma_f32_16x16x32_bf16 v[52:55], v[246:249], v[184:187], 0
	ds_read_b128 v[246:249], v133 offset:30528
	v_add_f32_e32 v36, v234, v36
	v_add_f32_e32 v39, v234, v39
	s_nop 0
	v_add_f32_e32 v32, v234, v32
	v_mfma_f32_16x16x32_bf16 v[56:59], v[56:59], v[184:187], 0
	v_add_f32_e32 v33, v234, v33
	v_mfma_f32_16x16x32_bf16 v[60:63], v[60:63], v[184:187], 0
	v_mfma_f32_16x16x32_bf16 v[48:51], v[64:67], v[184:187], 0
	v_mfma_f32_16x16x32_bf16 v[52:55], v[68:71], v[188:191], v[52:55]
	s_waitcnt lgkmcnt(2)
	v_mfma_f32_16x16x32_bf16 v[56:59], v[100:103], v[188:191], v[56:59]
	ds_read_b128 v[100:103], v133 offset:17536
	s_waitcnt lgkmcnt(2)
	v_mfma_f32_16x16x32_bf16 v[60:63], v[104:107], v[188:191], v[60:63]
	ds_read_b128 v[104:107], v133 offset:21888
	s_waitcnt lgkmcnt(2)
	v_mfma_f32_16x16x32_bf16 v[48:51], v[246:249], v[188:191], v[48:51]
	ds_read_b128 v[246:249], v133 offset:26240
	s_waitcnt lgkmcnt(2)
	v_mfma_f32_16x16x32_bf16 v[52:55], v[100:103], v[192:195], v[52:55]
	ds_read_b128 v[100:103], v133 offset:30592
	s_waitcnt lgkmcnt(2)
	v_mfma_f32_16x16x32_bf16 v[56:59], v[104:107], v[192:195], v[56:59]
	ds_read_b128 v[104:107], v133 offset:17600
	s_waitcnt lgkmcnt(2)
	v_mfma_f32_16x16x32_bf16 v[68:71], v[246:249], v[192:195], v[60:63]
	ds_read_b128 v[246:249], v133 offset:21952
	s_nop 2
	s_waitcnt lgkmcnt(2)
	v_mfma_f32_16x16x32_bf16 v[48:51], v[100:103], v[192:195], v[48:51]
	ds_read_b128 v[100:103], v133 offset:26304
	s_waitcnt lgkmcnt(2)
	v_mfma_f32_16x16x32_bf16 v[60:63], v[104:107], v[196:199], v[52:55]
	ds_read_b128 v[104:107], v133 offset:30656
	s_nop 2
	s_waitcnt lgkmcnt(2)
	v_mfma_f32_16x16x32_bf16 v[56:59], v[246:249], v[196:199], v[56:59]
	ds_read_b128 v[246:249], v133 offset:34816
	s_nop 6
	v_pk_add_f32 v[56:57], v[236:237], v[56:57] op_sel_hi:[0,1]
	s_waitcnt lgkmcnt(2)
	v_mfma_f32_16x16x32_bf16 v[52:55], v[100:103], v[196:199], v[68:71]
	ds_read_b128 v[100:103], v133 offset:39232
	s_nop 2
	v_pk_add_f32 v[58:59], v[236:237], v[58:59] op_sel_hi:[0,1]
	s_waitcnt lgkmcnt(2)
	v_mfma_f32_16x16x32_bf16 v[48:51], v[104:107], v[196:199], v[48:51]
	ds_read_b128 v[104:107], v133 offset:43584
	s_waitcnt lgkmcnt(2)
	v_mfma_f32_16x16x32_bf16 v[68:71], v[246:249], v[200:203], 0
	ds_read_b128 v[246:249], v133 offset:47936
	v_mfma_f32_16x16x32_bf16 v[72:75], v[72:75], v[200:203], 0
	v_mfma_f32_16x16x32_bf16 v[76:79], v[76:79], v[200:203], 0
	v_mfma_f32_16x16x32_bf16 v[64:67], v[80:83], v[200:203], 0
	v_mfma_f32_16x16x32_bf16 v[68:71], v[84:87], v[204:207], v[68:71]
	s_waitcnt lgkmcnt(2)
	v_mfma_f32_16x16x32_bf16 v[72:75], v[100:103], v[204:207], v[72:75]
	ds_read_b128 v[100:103], v133 offset:34944
	s_waitcnt lgkmcnt(2)
	v_mfma_f32_16x16x32_bf16 v[76:79], v[104:107], v[204:207], v[76:79]
	ds_read_b128 v[104:107], v133 offset:39296
	s_waitcnt lgkmcnt(2)
	v_mfma_f32_16x16x32_bf16 v[64:67], v[246:249], v[204:207], v[64:67]
	ds_read_b128 v[246:249], v133 offset:43648
	s_waitcnt lgkmcnt(2)
	v_mfma_f32_16x16x32_bf16 v[68:71], v[100:103], v[214:217], v[68:71]
	ds_read_b128 v[100:103], v133 offset:48000
	s_waitcnt lgkmcnt(2)
	v_mfma_f32_16x16x32_bf16 v[72:75], v[104:107], v[214:217], v[72:75]
	ds_read_b128 v[104:107], v133 offset:35008
	s_waitcnt lgkmcnt(2)
	v_mfma_f32_16x16x32_bf16 v[84:87], v[246:249], v[214:217], v[76:79]
	ds_read_b128 v[246:249], v133 offset:39360
	s_nop 2
	s_waitcnt lgkmcnt(2)
	v_mfma_f32_16x16x32_bf16 v[80:83], v[100:103], v[214:217], v[64:67]
	ds_read_b128 v[100:103], v133 offset:48064
	s_nop 2
	s_waitcnt lgkmcnt(2)
	v_mfma_f32_16x16x32_bf16 v[76:79], v[104:107], v[168:171], v[68:71]
	ds_read_b128 v[104:107], v133 offset:43712
	s_nop 1
	s_waitcnt lgkmcnt(1)
	v_mfma_f32_16x16x32_bf16 v[68:71], v[100:103], v[168:171], v[80:83]
	s_nop 2
	s_waitcnt lgkmcnt(2)
	v_mfma_f32_16x16x32_bf16 v[72:75], v[246:249], v[168:171], v[72:75]
	ds_read_b128 v[246:249], v133 offset:52224
	ds_read_b128 v[100:103], v133 offset:56576
	s_waitcnt lgkmcnt(2)
	v_mfma_f32_16x16x32_bf16 v[64:67], v[104:107], v[168:171], v[84:87]
	ds_read_b128 v[104:107], v133 offset:56640
	s_nop 2
	v_pk_add_f32 v[72:73], v[238:239], v[72:73] op_sel_hi:[0,1]
	s_waitcnt lgkmcnt(2)
	v_mfma_f32_16x16x32_bf16 v[84:87], v[246:249], v[218:221], 0
	ds_read_b128 v[246:249], v133 offset:60992
	v_add_f32_e64 v74, v238, v74
	v_add_f32_e64 v75, v238, v75
	s_waitcnt lgkmcnt(2)
	v_mfma_f32_16x16x32_bf16 v[88:91], v[100:103], v[218:221], 0
	ds_read_b128 v[100:103], v133 offset:65344
	v_mfma_f32_16x16x32_bf16 v[92:95], v[92:95], v[218:221], 0
	v_mfma_f32_16x16x32_bf16 v[80:83], v[154:157], v[218:221], 0
	v_mfma_f32_16x16x32_bf16 v[84:87], v[158:161], v[222:225], v[84:87]
	s_waitcnt lgkmcnt(2)
	v_mfma_f32_16x16x32_bf16 v[88:91], v[104:107], v[222:225], v[88:91]
	ds_read_b128 v[104:107], v133 offset:52352
	s_waitcnt lgkmcnt(2)
	v_mfma_f32_16x16x32_bf16 v[92:95], v[246:249], v[222:225], v[92:95]
	ds_read_b128 v[246:249], v133 offset:56704
	s_waitcnt lgkmcnt(2)
	v_mfma_f32_16x16x32_bf16 v[80:83], v[100:103], v[222:225], v[80:83]
	ds_read_b128 v[100:103], v133 offset:61056
	s_waitcnt lgkmcnt(2)
	v_mfma_f32_16x16x32_bf16 v[84:87], v[104:107], v[226:229], v[84:87]
	ds_read_b128 v[104:107], v133 offset:65408
	s_waitcnt lgkmcnt(2)
	v_mfma_f32_16x16x32_bf16 v[88:91], v[246:249], v[226:229], v[88:91]
	ds_read_b128 v[246:249], v133 offset:52416
	s_waitcnt lgkmcnt(2)
	v_mfma_f32_16x16x32_bf16 v[158:161], v[100:103], v[226:229], v[92:95]
	ds_read_b128 v[100:103], v133 offset:56768
	s_nop 2
	s_waitcnt lgkmcnt(2)
	v_mfma_f32_16x16x32_bf16 v[80:83], v[104:107], v[226:229], v[80:83]
	ds_read_b128 v[104:107], v133 offset:61120
	s_waitcnt lgkmcnt(2)
	v_mfma_f32_16x16x32_bf16 v[92:95], v[246:249], v[230:233], v[84:87]
	ds_read_b128 v[246:249], v133 offset:65472
	s_nop 2
	s_waitcnt lgkmcnt(2)
	v_mfma_f32_16x16x32_bf16 v[88:91], v[100:103], v[230:233], v[88:91]
	s_nop 6
	s_nop 0
	v_pk_add_f32 v[90:91], v[240:241], v[90:91] op_sel_hi:[0,1]
	s_waitcnt lgkmcnt(1)
	v_mfma_f32_16x16x32_bf16 v[84:87], v[104:107], v[230:233], v[158:161]
	s_nop 2
	v_pk_add_f32 v[88:89], v[240:241], v[88:89] op_sel_hi:[0,1]
	s_waitcnt lgkmcnt(0)
	v_mfma_f32_16x16x32_bf16 v[80:83], v[246:249], v[230:233], v[80:83]
	s_waitcnt vmcnt(0)
	v_lshlrev_b32_e32 v154, 16, v152
	v_and_b32_e32 v155, 0xffff0000, v152
	v_pk_mul_f32 v[44:45], v[44:45], v[154:155]
	v_lshlrev_b32_e32 v154, 16, v148
	v_and_b32_e32 v155, 0xffff0000, v148
	v_lshlrev_b32_e32 v148, 16, v149
	v_and_b32_e32 v149, 0xffff0000, v149
	v_pk_mul_f32 v[42:43], v[42:43], v[148:149]
	v_pk_mul_f32 v[40:41], v[40:41], v[154:155]
	v_mul_f32_e32 v148, v43, v43
	v_pk_fma_f32 v[154:155], v[42:43], v[42:43], v[148:149] op_sel_hi:[1,1,0]
	v_lshlrev_b32_e32 v148, 16, v146
	v_and_b32_e32 v146, 0xffff0000, v146
	v_mul_f32_e32 v146, v37, v146
	v_lshlrev_b32_e32 v37, 16, v147
	v_mul_f32_e32 v38, v38, v37
	v_and_b32_e32 v37, 0xffff0000, v147
	v_lshlrev_b32_e32 v152, 16, v153
	v_and_b32_e32 v153, 0xffff0000, v153
	v_mul_f32_e32 v36, v36, v148
	v_mul_f32_e32 v148, v39, v37
	v_lshlrev_b32_e32 v37, 16, v144
	v_pk_mul_f32 v[46:47], v[46:47], v[152:153]
	v_mul_f32_e32 v151, v32, v37
	v_and_b32_e32 v32, 0xffff0000, v144
	v_mul_f32_e32 v152, v47, v47
	v_mul_f32_e32 v33, v33, v32
	v_mul_f32_e32 v32, v45, v45
	v_pk_fma_f32 v[152:153], v[46:47], v[46:47], v[152:153] op_sel_hi:[1,1,0]
	v_pk_fma_f32 v[160:161], v[44:45], v[44:45], v[32:33] op_sel_hi:[1,1,0]
	v_add_f32_e32 v37, v234, v34
	v_add_f32_e32 v39, v234, v35
	v_mov_b32_e32 v150, v160
	v_mov_b32_e32 v162, v152
	v_mov_b32_e32 v163, v151
	v_pk_add_f32 v[152:153], v[160:161], v[152:153]
	v_pk_mul_f32 v[160:161], v[150:151], v[162:163]
	v_mul_f32_e32 v32, v41, v41
	v_mov_b32_e32 v153, v161
	v_pk_fma_f32 v[160:161], v[40:41], v[40:41], v[32:33] op_sel_hi:[1,1,0]
	v_mov_b32_e32 v162, v154
	v_mov_b32_e32 v32, v160
	v_mov_b32_e32 v163, v33
	v_lshlrev_b32_e32 v157, 16, v145
	v_mov_b32_e32 v156, v36
	v_pk_add_f32 v[154:155], v[160:161], v[154:155]
	v_pk_mul_f32 v[160:161], v[32:33], v[162:163]
	v_and_b32_e32 v159, 0xffff0000, v145
	v_pk_mul_f32 v[34:35], v[36:37], v[156:157]
	v_mov_b32_e32 v147, v37
	v_mov_b32_e32 v156, v146
	v_mov_b32_e32 v158, v38
	v_mov_b32_e32 v155, v161
	v_pk_mul_f32 v[144:145], v[38:39], v[158:159]
	v_mov_b32_e32 v149, v39
	v_mov_b32_e32 v158, v148
	v_pk_add_f32 v[152:153], v[152:153], v[154:155]
	v_pk_fma_f32 v[154:155], v[146:147], v[156:157], v[34:35]
	v_pk_mul_f32 v[156:157], v[34:35], v[34:35]
	v_add_f32_e32 v34, v236, v52
	v_mov_b32_e32 v155, v157
	v_pk_fma_f32 v[156:157], v[148:149], v[158:159], v[144:145]
	v_pk_mul_f32 v[158:159], v[144:145], v[144:145]
	v_and_b32_e32 v161, 0xffff0000, v135
	v_mov_b32_e32 v157, v159
	v_pk_add_f32 v[154:155], v[154:155], v[156:157]
	v_mov_b32_e32 v157, v62
	v_mov_b32_e32 v62, v61
	v_pk_add_f32 v[154:155], v[152:153], v[154:155]
	v_lshlrev_b32_e32 v153, 16, v141
	v_lshlrev_b32_e32 v152, 16, v140
	v_mov_b32_e32 v156, v60
	v_and_b32_e32 v141, 0xffff0000, v141
	v_and_b32_e32 v140, 0xffff0000, v140
	v_pk_add_f32 v[60:61], v[236:237], v[62:63] op_sel_hi:[0,1]
	v_pk_add_f32 v[156:157], v[236:237], v[156:157] op_sel_hi:[0,1]
	v_pk_mul_f32 v[60:61], v[60:61], v[140:141]
	v_pk_mul_f32 v[152:153], v[156:157], v[152:153]
	v_pk_mul_f32 v[62:63], v[60:61], v[60:61]
	v_pk_add_f32 v[154:155], v[154:155], v[154:155] op_sel:[0,1] op_sel_hi:[1,0]
	v_pk_fma_f32 v[62:63], v[152:153], v[152:153], v[62:63]
	v_lshlrev_b32_e32 v159, 16, v135
	v_pk_add_f32 v[140:141], v[62:63], v[62:63] op_sel:[0,1] op_sel_hi:[1,0]
	v_lshlrev_b32_e32 v62, 16, v138
	v_and_b32_e32 v63, 0xffff0000, v138
	v_pk_mul_f32 v[56:57], v[56:57], v[62:63]
	v_lshlrev_b32_e32 v62, 16, v139
	v_and_b32_e32 v63, 0xffff0000, v139
	v_pk_mul_f32 v[58:59], v[58:59], v[62:63]
	v_mov_b32_e32 v162, v140
	v_mul_f32_e32 v32, v59, v59
	v_pk_fma_f32 v[156:157], v[58:59], v[58:59], v[32:33] op_sel_hi:[1,1,0]
	v_lshlrev_b32_e32 v32, 16, v136
	v_mul_f32_e32 v52, v34, v32
	v_and_b32_e32 v32, 0xffff0000, v136
	v_add_f32_e32 v34, v236, v53
	v_mul_f32_e32 v62, v34, v32
	v_lshlrev_b32_e32 v32, 16, v137
	v_add_f32_e32 v34, v236, v54
	v_mul_f32_e32 v136, v34, v32
	v_and_b32_e32 v32, 0xffff0000, v137
	v_add_f32_e32 v34, v236, v55
	v_mul_f32_e32 v138, v34, v32
	v_lshlrev_b32_e32 v32, 16, v134
	v_add_f32_e32 v34, v236, v48
	v_mul_f32_e32 v55, v34, v32
	v_and_b32_e32 v32, 0xffff0000, v134
	v_add_f32_e32 v34, v236, v49
	v_mov_b32_e32 v54, v154
	v_mov_b32_e32 v163, v55
	v_mul_f32_e32 v49, v34, v32
	v_pk_add_f32 v[140:141], v[154:155], v[140:141]
	v_pk_mul_f32 v[154:155], v[54:55], v[162:163]
	v_mul_f32_e32 v32, v57, v57
	v_mov_b32_e32 v141, v155
	v_pk_fma_f32 v[154:155], v[56:57], v[56:57], v[32:33] op_sel_hi:[1,1,0]
	v_mov_b32_e32 v162, v156
	v_mov_b32_e32 v48, v154
	v_mov_b32_e32 v163, v49
	v_add_f32_e32 v53, v236, v50
	v_mov_b32_e32 v158, v52
	v_pk_add_f32 v[154:155], v[154:155], v[156:157]
	v_pk_mul_f32 v[156:157], v[48:49], v[162:163]
	v_add_f32_e32 v137, v236, v51
	v_pk_mul_f32 v[50:51], v[52:53], v[158:159]
	v_mov_b32_e32 v63, v53
	v_mov_b32_e32 v158, v62
	v_mov_b32_e32 v160, v136
	v_mov_b32_e32 v155, v157
	v_pk_mul_f32 v[134:135], v[136:137], v[160:161]
	v_mov_b32_e32 v139, v137
	v_mov_b32_e32 v160, v138
	v_pk_add_f32 v[140:141], v[140:141], v[154:155]
	v_pk_fma_f32 v[154:155], v[62:63], v[158:159], v[50:51]
	v_pk_mul_f32 v[156:157], v[50:51], v[50:51]
	v_pk_mul_f32 v[158:159], v[134:135], v[134:135]
	v_mov_b32_e32 v155, v157
	v_pk_fma_f32 v[156:157], v[138:139], v[160:161], v[134:135]
	v_add_f32_e32 v34, v238, v64
	v_mov_b32_e32 v157, v159
	v_pk_add_f32 v[154:155], v[154:155], v[156:157]
	v_mov_b32_e32 v157, v78
	v_mov_b32_e32 v78, v77
	v_pk_add_f32 v[154:155], v[140:141], v[154:155]
	v_lshlrev_b32_e32 v141, 16, v131
	v_lshlrev_b32_e32 v140, 16, v130
	v_mov_b32_e32 v156, v76
	v_and_b32_e32 v131, 0xffff0000, v131
	v_and_b32_e32 v130, 0xffff0000, v130
	v_pk_add_f32 v[76:77], v[238:239], v[78:79] op_sel_hi:[0,1]
	v_pk_add_f32 v[156:157], v[238:239], v[156:157] op_sel_hi:[0,1]
	v_pk_mul_f32 v[76:77], v[76:77], v[130:131]
	v_pk_mul_f32 v[140:141], v[156:157], v[140:141]
	v_pk_mul_f32 v[78:79], v[76:77], v[76:77]
	v_pk_add_f32 v[154:155], v[154:155], v[154:155] op_sel:[0,1] op_sel_hi:[1,0]
	v_pk_fma_f32 v[78:79], v[140:141], v[140:141], v[78:79]
	v_lshlrev_b32_e32 v159, 16, v125
	v_pk_add_f32 v[130:131], v[78:79], v[78:79] op_sel:[0,1] op_sel_hi:[1,0]
	v_lshlrev_b32_e32 v78, 16, v128
	v_and_b32_e32 v79, 0xffff0000, v128
	v_pk_mul_f32 v[72:73], v[72:73], v[78:79]
	v_lshlrev_b32_e32 v78, 16, v129
	v_and_b32_e32 v79, 0xffff0000, v129
	v_pk_mul_f32 v[74:75], v[74:75], v[78:79]
	v_mov_b32_e32 v162, v130
	v_mul_f32_e32 v32, v75, v75
	v_pk_fma_f32 v[156:157], v[74:75], v[74:75], v[32:33] op_sel_hi:[1,1,0]
	v_lshlrev_b32_e32 v32, 16, v126
	v_mul_f32_e32 v64, v34, v32
	v_and_b32_e32 v32, 0xffff0000, v126
	v_add_f32_e32 v34, v238, v65
	v_mul_f32_e32 v78, v34, v32
	v_lshlrev_b32_e32 v32, 16, v127
	v_add_f32_e32 v34, v238, v66
	v_mul_f32_e32 v126, v34, v32
	v_and_b32_e32 v32, 0xffff0000, v127
	v_add_f32_e32 v34, v238, v67
	v_mul_f32_e32 v128, v34, v32
	v_lshlrev_b32_e32 v32, 16, v124
	v_add_f32_e32 v34, v238, v68
	v_mul_f32_e32 v67, v34, v32
	v_and_b32_e32 v32, 0xffff0000, v124
	v_add_f32_e32 v34, v238, v69
	v_mov_b32_e32 v66, v154
	v_mov_b32_e32 v163, v67
	v_mul_f32_e32 v69, v34, v32
	v_pk_add_f32 v[130:131], v[154:155], v[130:131]
	v_pk_mul_f32 v[154:155], v[66:67], v[162:163]
	v_mul_f32_e32 v32, v73, v73
	v_mov_b32_e32 v131, v155
	v_pk_fma_f32 v[154:155], v[72:73], v[72:73], v[32:33] op_sel_hi:[1,1,0]
	v_mov_b32_e32 v162, v156
	v_mov_b32_e32 v68, v154
	v_mov_b32_e32 v163, v69
	v_add_f32_e32 v65, v238, v70
	v_mov_b32_e32 v158, v64
	v_pk_add_f32 v[154:155], v[154:155], v[156:157]
	v_pk_mul_f32 v[156:157], v[68:69], v[162:163]
	v_and_b32_e32 v161, 0xffff0000, v125
	v_add_f32_e32 v127, v238, v71
	v_pk_mul_f32 v[70:71], v[64:65], v[158:159]
	v_mov_b32_e32 v79, v65
	v_mov_b32_e32 v158, v78
	v_mov_b32_e32 v160, v126
	v_mov_b32_e32 v155, v157
	v_pk_mul_f32 v[124:125], v[126:127], v[160:161]
	v_mov_b32_e32 v129, v127
	v_mov_b32_e32 v160, v128
	v_pk_add_f32 v[130:131], v[130:131], v[154:155]
	v_pk_fma_f32 v[154:155], v[78:79], v[158:159], v[70:71]
	v_pk_mul_f32 v[156:157], v[70:71], v[70:71]
	v_pk_mul_f32 v[158:159], v[124:125], v[124:125]
	v_mov_b32_e32 v155, v157
	v_pk_fma_f32 v[156:157], v[128:129], v[160:161], v[124:125]
	v_add_f32_e32 v34, v240, v84
	v_mov_b32_e32 v157, v159
	v_pk_add_f32 v[154:155], v[154:155], v[156:157]
	v_mov_b32_e32 v157, v94
	v_mov_b32_e32 v94, v93
	v_pk_add_f32 v[154:155], v[130:131], v[154:155]
	v_lshlrev_b32_e32 v131, 16, v121
	v_lshlrev_b32_e32 v130, 16, v120
	v_mov_b32_e32 v156, v92
	v_and_b32_e32 v121, 0xffff0000, v121
	v_and_b32_e32 v120, 0xffff0000, v120
	v_pk_add_f32 v[92:93], v[240:241], v[94:95] op_sel_hi:[0,1]
	v_pk_mul_f32 v[92:93], v[92:93], v[120:121]
	v_lshlrev_b32_e32 v120, 16, v118
	v_and_b32_e32 v121, 0xffff0000, v118
	v_lshlrev_b32_e32 v118, 16, v119
	v_and_b32_e32 v119, 0xffff0000, v119
	v_pk_mul_f32 v[90:91], v[90:91], v[118:119]
	v_pk_add_f32 v[156:157], v[240:241], v[156:157] op_sel_hi:[0,1]
	v_mul_f32_e32 v32, v91, v91
	v_pk_fma_f32 v[118:119], v[90:91], v[90:91], v[32:33] op_sel_hi:[1,1,0]
	v_lshlrev_b32_e32 v32, 16, v116
	v_mul_f32_e32 v84, v34, v32
	v_and_b32_e32 v32, 0xffff0000, v116
	v_add_f32_e32 v34, v240, v85
	v_mul_f32_e32 v116, v34, v32
	v_lshlrev_b32_e32 v32, 16, v117
	v_add_f32_e32 v34, v240, v86
	v_pk_mul_f32 v[130:131], v[156:157], v[130:131]
	v_pk_mul_f32 v[94:95], v[92:93], v[92:93]
	v_mul_f32_e32 v86, v34, v32
	v_and_b32_e32 v32, 0xffff0000, v117
	v_add_f32_e32 v34, v240, v87
	v_pk_fma_f32 v[94:95], v[130:131], v[130:131], v[94:95]
	v_pk_mul_f32 v[88:89], v[88:89], v[120:121]
	v_mul_f32_e32 v120, v34, v32
	v_lshlrev_b32_e32 v32, 16, v114
	v_add_f32_e32 v34, v240, v80
	v_pk_add_f32 v[94:95], v[94:95], v[94:95] op_sel:[0,1] op_sel_hi:[1,0]
	v_mul_f32_e32 v157, v34, v32
	v_pk_add_f32 v[154:155], v[154:155], v[154:155] op_sel:[0,1] op_sel_hi:[1,0]
	v_and_b32_e32 v32, 0xffff0000, v114
	v_add_f32_e32 v34, v240, v81
	v_mov_b32_e32 v156, v154
	v_mov_b32_e32 v162, v94
	v_mov_b32_e32 v163, v157
	v_mul_f32_e32 v81, v34, v32
	v_pk_add_f32 v[94:95], v[154:155], v[94:95]
	v_pk_mul_f32 v[154:155], v[156:157], v[162:163]
	v_mul_f32_e32 v32, v89, v89
	v_mov_b32_e32 v95, v155
	v_pk_fma_f32 v[154:155], v[88:89], v[88:89], v[32:33] op_sel_hi:[1,1,0]
	v_mov_b32_e32 v162, v118
	v_mov_b32_e32 v80, v154
	v_mov_b32_e32 v163, v81
	v_lshlrev_b32_e32 v159, 16, v115
	v_add_f32_e32 v85, v240, v82
	v_mov_b32_e32 v158, v84
	v_pk_add_f32 v[118:119], v[154:155], v[118:119]
	v_pk_mul_f32 v[154:155], v[80:81], v[162:163]
	v_and_b32_e32 v115, 0xffff0000, v115
	v_add_f32_e32 v87, v240, v83
	v_pk_mul_f32 v[82:83], v[84:85], v[158:159]
	v_mov_b32_e32 v117, v85
	v_mov_b32_e32 v158, v116
	v_mov_b32_e32 v114, v86
	v_mov_b32_e32 v119, v155
	v_pk_mul_f32 v[160:161], v[86:87], v[114:115]
	v_mov_b32_e32 v121, v87
	v_mov_b32_e32 v114, v120
	v_pk_add_f32 v[94:95], v[94:95], v[118:119]
	v_pk_fma_f32 v[118:119], v[116:117], v[158:159], v[82:83]
	v_pk_mul_f32 v[154:155], v[82:83], v[82:83]
	v_pk_fma_f32 v[114:115], v[120:121], v[114:115], v[160:161]
	v_mov_b32_e32 v119, v155
	v_pk_mul_f32 v[154:155], v[160:161], v[160:161]
	v_and_b32_e32 v37, 64, v245
	v_mov_b32_e32 v115, v155
	v_xor_b32_e32 v34, 16, v245
	v_add_u32_e32 v37, 64, v37
	v_pk_add_f32 v[114:115], v[118:119], v[114:115]
	v_cmp_lt_i32_e32 vcc, v34, v37
	v_pk_add_f32 v[94:95], v[94:95], v[114:115]
	s_nop 0
	v_cndmask_b32_e32 v34, v245, v34, vcc
	v_add_f32_e32 v32, v94, v95
	v_lshlrev_b32_e32 v34, 2, v34
	ds_bpermute_b32 v34, v34, v32
	v_lshl_add_u64 v[94:95], v[112:113], 0, v[208:209]
	v_lshl_add_u64 v[112:113], v[94:95], 0, s[18:19]
	s_waitcnt lgkmcnt(0)
	v_add_f32_e32 v32, v32, v34
	v_xor_b32_e32 v34, 32, v245
	v_cmp_lt_i32_e32 vcc, v34, v37
	s_nop 1
	v_cndmask_b32_e32 v34, v245, v34, vcc
	v_lshlrev_b32_e32 v34, 2, v34
	ds_bpermute_b32 v34, v34, v32
	s_waitcnt lgkmcnt(0)
	v_add_f32_e32 v32, v32, v34
	v_fmamk_f32 v32, v32, 0x3b800000, v244
	v_cmp_gt_f32_e32 vcc, s7, v32
	v_mul_f32_e32 v34, 0x4b800000, v32
	s_nop 0
	v_cndmask_b32_e32 v32, v32, v34, vcc
	v_rsq_f32_e32 v32, v32
	s_nop 0
	v_mul_f32_e32 v34, 0x45800000, v32
	v_cndmask_b32_e32 v34, v32, v34, vcc
	v_mbcnt_lo_u32_b32 v246, -1, 0
	v_mbcnt_hi_u32_b32 v246, -1, v246
	v_lshrrev_b32_e32 v246, 4, v246
	v_and_b32_e32 v246, 1, v246
	v_mul_u32_u24_e32 v246, 24, v246
	v_mov_b32_e32 v247, v209
	v_lshl_add_u64 v[248:249], v[112:113], 0, v[246:247]
	v_mul_f32_e32 v44, v44, v34
	v_mul_f32_e32 v45, v45, v34
	v_cvt_pk_bf16_f32 v100, v44, v45
	v_mul_f32_e32 v46, v46, v34
	v_mul_f32_e32 v47, v47, v34
	v_cvt_pk_bf16_f32 v101, v46, v47
	v_mul_f32_e32 v40, v40, v34
	v_mul_f32_e32 v41, v41, v34
	v_cvt_pk_bf16_f32 v102, v40, v41
	v_mul_f32_e32 v42, v42, v34
	v_mul_f32_e32 v43, v43, v34
	v_cvt_pk_bf16_f32 v103, v42, v43
	s_nop 1
	v_permlane16_swap_b32_e32 v100, v102
	v_permlane16_swap_b32_e32 v101, v103
	global_store_dwordx4 v[248:249], v[100:103], off
	v_mul_f32_e32 v36, v36, v34
	v_mul_f32_e32 v146, v146, v34
	v_cvt_pk_bf16_f32 v104, v36, v146
	v_mul_f32_e32 v38, v38, v34
	v_mul_f32_e32 v148, v148, v34
	v_cvt_pk_bf16_f32 v105, v38, v148
	v_mul_f32_e32 v151, v151, v34
	v_mul_f32_e32 v33, v33, v34
	v_cvt_pk_bf16_f32 v106, v151, v33
	v_mul_f32_e32 v35, v35, v34
	v_mul_f32_e32 v145, v145, v34
	v_cvt_pk_bf16_f32 v107, v35, v145
	s_nop 1
	v_permlane16_swap_b32_e32 v104, v106
	v_permlane16_swap_b32_e32 v105, v107
	global_store_dwordx4 v[248:249], v[104:107], off offset:64
	v_mul_f32_e32 v152, v152, v34
	v_mul_f32_e32 v60, v60, v34
	v_cvt_pk_bf16_f32 v100, v152, v60
	v_mul_f32_e32 v153, v153, v34
	v_mul_f32_e32 v61, v61, v34
	v_cvt_pk_bf16_f32 v101, v153, v61
	v_mul_f32_e32 v56, v56, v34
	v_mul_f32_e32 v57, v57, v34
	v_cvt_pk_bf16_f32 v102, v56, v57
	v_mul_f32_e32 v58, v58, v34
	v_mul_f32_e32 v59, v59, v34
	v_cvt_pk_bf16_f32 v103, v58, v59
	s_nop 1
	v_permlane16_swap_b32_e32 v100, v102
	v_permlane16_swap_b32_e32 v101, v103
	global_store_dwordx4 v[248:249], v[100:103], off offset:128
	v_mul_f32_e32 v52, v52, v34
	v_mul_f32_e32 v62, v62, v34
	v_cvt_pk_bf16_f32 v104, v52, v62
	v_mul_f32_e32 v136, v136, v34
	v_mul_f32_e32 v138, v138, v34
	v_cvt_pk_bf16_f32 v105, v136, v138
	v_mul_f32_e32 v55, v55, v34
	v_mul_f32_e32 v49, v49, v34
	v_cvt_pk_bf16_f32 v106, v55, v49
	v_mul_f32_e32 v51, v51, v34
	v_mul_f32_e32 v135, v135, v34
	v_cvt_pk_bf16_f32 v107, v51, v135
	s_nop 1
	v_permlane16_swap_b32_e32 v104, v106
	v_permlane16_swap_b32_e32 v105, v107
	global_store_dwordx4 v[248:249], v[104:107], off offset:192
	v_mul_f32_e32 v140, v140, v34
	v_mul_f32_e32 v76, v76, v34
	v_cvt_pk_bf16_f32 v100, v140, v76
	v_mul_f32_e32 v141, v141, v34
	v_mul_f32_e32 v77, v77, v34
	v_cvt_pk_bf16_f32 v101, v141, v77
	v_mul_f32_e32 v72, v72, v34
	v_mul_f32_e32 v73, v73, v34
	v_cvt_pk_bf16_f32 v102, v72, v73
	v_mul_f32_e32 v74, v74, v34
	v_mul_f32_e32 v75, v75, v34
	v_cvt_pk_bf16_f32 v103, v74, v75
	s_nop 1
	v_permlane16_swap_b32_e32 v100, v102
	v_permlane16_swap_b32_e32 v101, v103
	global_store_dwordx4 v[248:249], v[100:103], off offset:256
	v_mul_f32_e32 v64, v64, v34
	v_mul_f32_e32 v78, v78, v34
	v_cvt_pk_bf16_f32 v104, v64, v78
	v_mul_f32_e32 v126, v126, v34
	v_mul_f32_e32 v128, v128, v34
	v_cvt_pk_bf16_f32 v105, v126, v128
	v_mul_f32_e32 v67, v67, v34
	v_mul_f32_e32 v69, v69, v34
	v_cvt_pk_bf16_f32 v106, v67, v69
	v_mul_f32_e32 v71, v71, v34
	v_mul_f32_e32 v125, v125, v34
	v_cvt_pk_bf16_f32 v107, v71, v125
	s_nop 1
	v_permlane16_swap_b32_e32 v104, v106
	v_permlane16_swap_b32_e32 v105, v107
	global_store_dwordx4 v[248:249], v[104:107], off offset:320
	v_mul_f32_e32 v130, v130, v34
	v_mul_f32_e32 v92, v92, v34
	v_cvt_pk_bf16_f32 v100, v130, v92
	v_mul_f32_e32 v131, v131, v34
	v_mul_f32_e32 v93, v93, v34
	v_cvt_pk_bf16_f32 v101, v131, v93
	v_mul_f32_e32 v88, v88, v34
	v_mul_f32_e32 v89, v89, v34
	v_cvt_pk_bf16_f32 v102, v88, v89
	v_mul_f32_e32 v90, v90, v34
	v_mul_f32_e32 v91, v91, v34
	v_cvt_pk_bf16_f32 v103, v90, v91
	s_nop 1
	v_permlane16_swap_b32_e32 v100, v102
	v_permlane16_swap_b32_e32 v101, v103
	global_store_dwordx4 v[248:249], v[100:103], off offset:384
	v_mul_f32_e32 v84, v84, v34
	v_mul_f32_e32 v116, v116, v34
	v_cvt_pk_bf16_f32 v104, v84, v116
	v_mul_f32_e32 v86, v86, v34
	v_mul_f32_e32 v120, v120, v34
	v_cvt_pk_bf16_f32 v105, v86, v120
	v_mul_f32_e32 v157, v157, v34
	v_mul_f32_e32 v81, v81, v34
	v_cvt_pk_bf16_f32 v106, v157, v81
	v_mul_f32_e32 v83, v83, v34
	v_mul_f32_e32 v161, v161, v34
	v_cvt_pk_bf16_f32 v107, v83, v161
	s_nop 1
	v_permlane16_swap_b32_e32 v104, v106
	v_permlane16_swap_b32_e32 v105, v107
	global_store_dwordx4 v[248:249], v[104:107], off offset:448
	s_barrier
	s_cbranch_scc0 .LBB0_242

.LBB0_362:
	global_load_dwordx4 v[104:107], v[80:81], off
	global_load_dwordx4 v[116:119], v[80:81], off offset:2048
	global_load_dwordx4 v[120:123], v[82:83], off
	global_load_dwordx4 v[132:135], v[84:85], off
	s_ashr_i32 s11, s3, 31
	s_lshr_b32 s11, s11, 19
	s_add_i32 s11, s3, s11
	s_and_b32 s11, s11, 0xffffe000
	s_sub_i32 s11, s3, s11
	v_or_b32_e32 v0, s11, v158
	s_ashr_i32 s11, s0, 31
	s_lshr_b32 s11, s11, 23
	s_add_i32 s11, s0, s11
	s_ashr_i32 s11, s11, 9
	s_mul_i32 s18, s11, 0x84
	s_ashr_i32 s19, s18, 31
	v_sub_u32_e32 v1, 0, v0
	s_lshl_b64 s[18:19], s[18:19], 15
	v_and_b32_e32 v2, 0x1fff, v1
	v_ashrrev_i32_e32 v1, 31, v0
	s_add_u32 s22, s16, s18
	s_addc_u32 s23, s33, s19
	v_lshlrev_b64 v[56:57], 2, v[0:1]
	v_lshl_add_u64 v[22:23], s[22:23], 0, v[56:57]
	v_lshlrev_b32_e32 v208, 2, v2
	v_lshl_add_u64 v[0:1], v[22:23], 0, v[64:65]
	v_lshl_add_u64 v[2:3], v[22:23], 0, v[66:67]
	v_lshl_add_u64 v[4:5], v[22:23], 0, v[68:69]
	v_lshl_add_u64 v[6:7], v[22:23], 0, v[70:71]
	v_lshl_add_u64 v[8:9], v[22:23], 0, v[72:73]
	v_lshl_add_u64 v[10:11], v[22:23], 0, v[74:75]
	v_lshl_add_u64 v[12:13], v[22:23], 0, v[76:77]
	v_lshl_add_u64 v[14:15], v[22:23], 0, v[78:79]
	global_load_dword v2, v[2:3], off
	s_nop 0
	global_load_dword v0, v[0:1], off
	s_nop 0
	global_load_dword v1, v[6:7], off
	global_load_dword v3, v[4:5], off
	s_nop 0
	global_load_dword v4, v[10:11], off
	global_load_dword v5, v[8:9], off
	global_load_dword v6, v[14:15], off
	global_load_dword v7, v[12:13], off
	v_lshl_add_u64 v[20:21], s[22:23], 0, v[208:209]
	v_lshl_add_u64 v[24:25], v[20:21], 0, v[94:95]
	v_lshl_add_u64 v[26:27], v[20:21], 0, v[96:97]
	v_lshl_add_u64 v[28:29], v[20:21], 0, v[98:99]
	v_lshl_add_u64 v[30:31], v[20:21], 0, v[100:101]
	s_add_u32 s18, s22, 0x108000
	s_addc_u32 s19, s23, 0
	v_lshl_add_u64 v[38:39], s[18:19], 0, v[56:57]
	v_lshl_add_u64 v[36:37], s[18:19], 0, v[208:209]
	v_lshl_add_u64 v[40:41], v[36:37], 0, v[94:95]
	v_lshl_add_u64 v[42:43], v[36:37], 0, v[96:97]
	v_lshl_add_u64 v[44:45], v[36:37], 0, v[98:99]
	v_lshl_add_u64 v[46:47], v[36:37], 0, v[100:101]
	s_add_u32 s18, s22, 0x210000
	s_addc_u32 s19, s23, 0
	v_lshl_add_u64 v[54:55], s[18:19], 0, v[56:57]
	v_lshl_add_u64 v[52:53], s[18:19], 0, v[208:209]
	v_lshl_add_u64 v[58:59], v[52:53], 0, v[94:95]
	v_lshl_add_u64 v[60:61], v[52:53], 0, v[96:97]
	v_lshl_add_u64 v[62:63], v[52:53], 0, v[98:99]
	v_lshl_add_u64 v[160:161], v[52:53], 0, v[100:101]
	s_add_u32 s18, s22, 0x318000
	s_addc_u32 s19, s23, 0
	v_lshl_add_u64 v[166:167], s[18:19], 0, v[56:57]
	v_lshl_add_u64 v[56:57], v[166:167], 0, v[72:73]
	v_lshl_add_u64 v[164:165], s[18:19], 0, v[208:209]
	v_lshl_add_u64 v[168:169], v[164:165], 0, v[94:95]
	v_lshl_add_u64 v[170:171], v[164:165], 0, v[96:97]
	v_lshl_add_u64 v[172:173], v[164:165], 0, v[98:99]
	v_lshl_add_u64 v[174:175], v[164:165], 0, v[100:101]
	s_mov_b64 s[18:19], 0x1a000400
	s_add_i32 s0, s0, s2
	s_waitcnt vmcnt(6)
	v_cvt_pk_bf16_f32 v0, v0, v2
	s_waitcnt vmcnt(4)
	v_cvt_pk_bf16_f32 v1, v3, v1
	s_waitcnt vmcnt(2)
	v_cvt_pk_bf16_f32 v2, v5, v4
	s_waitcnt vmcnt(0)
	v_cvt_pk_bf16_f32 v3, v7, v6
	s_waitcnt vmcnt(3)
	v_mfma_f32_16x16x32_bf16 v[4:7], v[104:107], v[0:3], 0
	s_waitcnt vmcnt(2)
	v_mfma_f32_16x16x32_bf16 v[8:11], v[116:119], v[0:3], 0
	s_waitcnt vmcnt(1)
	v_mfma_f32_16x16x32_bf16 v[12:15], v[120:123], v[0:3], 0
	s_waitcnt vmcnt(0)
	v_mfma_f32_16x16x32_bf16 v[0:3], v[132:135], v[0:3], 0
	global_load_dwordx4 v[104:107], v[112:113], off
	global_load_dwordx4 v[116:119], v[108:109], off
	global_load_dwordx4 v[120:123], v[110:111], off
	global_load_dwordx4 v[132:135], v[114:115], off
	v_lshl_add_u64 v[16:17], v[22:23], 0, v[88:89]
	v_lshl_add_u64 v[18:19], v[20:21], 0, v[86:87]
	v_cndmask_b32_e32 v17, v19, v17, vcc
	v_cndmask_b32_e32 v16, v18, v16, vcc
	v_lshl_add_u64 v[18:19], v[20:21], 0, v[90:91]
	v_lshl_add_u64 v[22:23], v[20:21], 0, v[92:93]
	v_lshl_add_u64 v[20:21], v[20:21], 0, v[102:103]
	global_load_dword v16, v[16:17], off
	s_nop 0
	global_load_dword v17, v[18:19], off
	s_nop 0
	global_load_dword v18, v[24:25], off
	global_load_dword v19, v[22:23], off
	s_nop 0
	global_load_dword v22, v[28:29], off
	global_load_dword v23, v[26:27], off
	s_nop 0
	global_load_dword v20, v[20:21], off
	s_nop 0
	global_load_dword v21, v[30:31], off
	v_lshl_add_u64 v[28:29], v[38:39], 0, v[76:77]
	v_lshl_add_u64 v[30:31], v[38:39], 0, v[78:79]
	s_waitcnt vmcnt(6)
	v_cvt_pk_bf16_f32 v16, v16, v17
	s_waitcnt vmcnt(4)
	v_cvt_pk_bf16_f32 v17, v19, v18
	s_waitcnt vmcnt(2)
	v_cvt_pk_bf16_f32 v18, v23, v22
	s_waitcnt vmcnt(0)
	v_cvt_pk_bf16_f32 v19, v21, v20
	s_waitcnt vmcnt(0)
	v_mfma_f32_16x16x32_bf16 v[24:27], v[176:179], v[16:19], v[4:7]
	s_nop 2
	v_lshl_add_u64 v[20:21], v[38:39], 0, v[72:73]
	v_lshl_add_u64 v[22:23], v[38:39], 0, v[74:75]
	s_waitcnt vmcnt(0)
	v_mfma_f32_16x16x32_bf16 v[8:11], v[180:183], v[16:19], v[8:11]
	s_waitcnt vmcnt(0)
	v_mfma_f32_16x16x32_bf16 v[4:7], v[184:187], v[16:19], v[12:15]
	s_nop 2
	s_waitcnt vmcnt(0)
	v_mfma_f32_16x16x32_bf16 v[0:3], v[188:191], v[16:19], v[0:3]
	v_lshl_add_u64 v[12:13], v[38:39], 0, v[64:65]
	v_lshl_add_u64 v[14:15], v[38:39], 0, v[66:67]
	v_lshl_add_u64 v[16:17], v[38:39], 0, v[68:69]
	v_lshl_add_u64 v[18:19], v[38:39], 0, v[70:71]
	global_load_dword v14, v[14:15], off
	s_nop 0
	global_load_dword v12, v[12:13], off
	s_nop 0
	global_load_dword v13, v[18:19], off
	global_load_dword v15, v[16:17], off
	s_nop 0
	global_load_dword v16, v[22:23], off
	global_load_dword v17, v[20:21], off
	global_load_dword v18, v[30:31], off
	global_load_dword v19, v[28:29], off
	s_waitcnt vmcnt(6)
	v_cvt_pk_bf16_f32 v12, v12, v14
	s_waitcnt vmcnt(4)
	v_cvt_pk_bf16_f32 v13, v15, v13
	s_waitcnt vmcnt(2)
	v_cvt_pk_bf16_f32 v14, v17, v16
	s_waitcnt vmcnt(0)
	v_cvt_pk_bf16_f32 v15, v19, v18
	s_waitcnt vmcnt(2)
	v_mfma_f32_16x16x32_bf16 v[32:35], v[104:107], v[12:15], 0
	s_waitcnt vmcnt(2)
	v_mfma_f32_16x16x32_bf16 v[16:19], v[116:119], v[12:15], 0
	s_waitcnt vmcnt(1)
	v_mfma_f32_16x16x32_bf16 v[20:23], v[120:123], v[12:15], 0
	s_waitcnt vmcnt(0)
	v_mfma_f32_16x16x32_bf16 v[12:15], v[132:135], v[12:15], 0
	global_load_dwordx4 v[104:107], v[128:129], off
	global_load_dwordx4 v[116:119], v[124:125], off
	global_load_dwordx4 v[120:123], v[126:127], off
	global_load_dwordx4 v[132:135], v[130:131], off
	v_lshl_add_u64 v[28:29], v[38:39], 0, v[88:89]
	v_lshl_add_u64 v[30:31], v[36:37], 0, v[86:87]
	v_cndmask_b32_e32 v29, v31, v29, vcc
	v_cndmask_b32_e32 v28, v30, v28, vcc
	v_lshl_add_u64 v[30:31], v[36:37], 0, v[90:91]
	v_lshl_add_u64 v[38:39], v[36:37], 0, v[92:93]
	v_lshl_add_u64 v[36:37], v[36:37], 0, v[102:103]
	global_load_dword v28, v[28:29], off
	s_nop 0
	global_load_dword v29, v[30:31], off
	s_nop 0
	global_load_dword v30, v[40:41], off
	global_load_dword v31, v[38:39], off
	s_nop 0
	global_load_dword v38, v[44:45], off
	global_load_dword v39, v[42:43], off
	global_load_dword v40, v[36:37], off
	global_load_dword v41, v[46:47], off
	v_lshl_add_u64 v[42:43], v[54:55], 0, v[74:75]
	v_lshl_add_u64 v[44:45], v[54:55], 0, v[76:77]
	v_lshl_add_u64 v[46:47], v[54:55], 0, v[78:79]
	s_waitcnt vmcnt(6)
	v_cvt_pk_bf16_f32 v36, v28, v29
	s_waitcnt vmcnt(4)
	v_cvt_pk_bf16_f32 v37, v31, v30
	s_waitcnt vmcnt(2)
	v_cvt_pk_bf16_f32 v38, v39, v38
	s_waitcnt vmcnt(0)
	v_cvt_pk_bf16_f32 v39, v41, v40
	v_lshl_add_u64 v[40:41], v[54:55], 0, v[72:73]
	s_waitcnt vmcnt(0)
	v_mfma_f32_16x16x32_bf16 v[28:31], v[192:195], v[36:39], v[16:19]
	s_nop 2
	s_waitcnt vmcnt(0)
	v_mfma_f32_16x16x32_bf16 v[20:23], v[196:199], v[36:39], v[20:23]
	s_waitcnt vmcnt(0)
	v_mfma_f32_16x16x32_bf16 v[16:19], v[200:203], v[36:39], v[32:35]
	s_nop 2
	s_waitcnt vmcnt(0)
	v_mfma_f32_16x16x32_bf16 v[12:15], v[204:207], v[36:39], v[12:15]
	v_lshl_add_u64 v[32:33], v[54:55], 0, v[64:65]
	v_lshl_add_u64 v[34:35], v[54:55], 0, v[66:67]
	v_lshl_add_u64 v[36:37], v[54:55], 0, v[68:69]
	v_lshl_add_u64 v[38:39], v[54:55], 0, v[70:71]
	global_load_dword v34, v[34:35], off
	s_nop 0
	global_load_dword v32, v[32:33], off
	s_nop 0
	global_load_dword v33, v[38:39], off
	global_load_dword v35, v[36:37], off
	s_nop 0
	global_load_dword v36, v[42:43], off
	global_load_dword v37, v[40:41], off
	global_load_dword v38, v[46:47], off
	global_load_dword v39, v[44:45], off
	s_waitcnt vmcnt(6)
	v_cvt_pk_bf16_f32 v32, v32, v34
	s_waitcnt vmcnt(4)
	v_cvt_pk_bf16_f32 v33, v35, v33
	s_waitcnt vmcnt(2)
	v_cvt_pk_bf16_f32 v34, v37, v36
	s_waitcnt vmcnt(0)
	v_cvt_pk_bf16_f32 v35, v39, v38
	s_waitcnt vmcnt(2)
	v_mfma_f32_16x16x32_bf16 v[48:51], v[104:107], v[32:35], 0
	s_waitcnt vmcnt(2)
	v_mfma_f32_16x16x32_bf16 v[36:39], v[116:119], v[32:35], 0
	s_waitcnt vmcnt(1)
	v_mfma_f32_16x16x32_bf16 v[40:43], v[120:123], v[32:35], 0
	s_waitcnt vmcnt(0)
	v_mfma_f32_16x16x32_bf16 v[32:35], v[132:135], v[32:35], 0
	global_load_dwordx4 v[104:107], v[144:145], off
	global_load_dwordx4 v[116:119], v[140:141], off
	global_load_dwordx4 v[120:123], v[142:143], off
	global_load_dwordx4 v[132:135], v[146:147], off
	v_lshl_add_u64 v[44:45], v[54:55], 0, v[88:89]
	v_lshl_add_u64 v[46:47], v[52:53], 0, v[86:87]
	v_cndmask_b32_e32 v45, v47, v45, vcc
	v_cndmask_b32_e32 v44, v46, v44, vcc
	v_lshl_add_u64 v[46:47], v[52:53], 0, v[90:91]
	v_lshl_add_u64 v[54:55], v[52:53], 0, v[92:93]
	v_lshl_add_u64 v[52:53], v[52:53], 0, v[102:103]
	global_load_dword v44, v[44:45], off
	s_nop 0
	global_load_dword v45, v[46:47], off
	s_nop 0
	global_load_dword v46, v[58:59], off
	global_load_dword v47, v[54:55], off
	s_nop 0
	global_load_dword v54, v[62:63], off
	global_load_dword v55, v[60:61], off
	global_load_dword v58, v[52:53], off
	global_load_dword v59, v[160:161], off
	v_lshl_add_u64 v[60:61], v[166:167], 0, v[76:77]
	v_lshl_add_u64 v[62:63], v[166:167], 0, v[78:79]
	s_waitcnt vmcnt(6)
	v_cvt_pk_bf16_f32 v52, v44, v45
	s_waitcnt vmcnt(4)
	v_cvt_pk_bf16_f32 v53, v47, v46
	s_waitcnt vmcnt(2)
	v_cvt_pk_bf16_f32 v54, v55, v54
	s_waitcnt vmcnt(0)
	v_cvt_pk_bf16_f32 v55, v59, v58
	v_lshl_add_u64 v[58:59], v[166:167], 0, v[74:75]
	s_waitcnt vmcnt(0)
	v_mfma_f32_16x16x32_bf16 v[44:47], v[214:217], v[52:55], v[36:39]
	s_nop 2
	s_waitcnt vmcnt(0)
	v_mfma_f32_16x16x32_bf16 v[40:43], v[218:221], v[52:55], v[40:43]
	s_waitcnt vmcnt(0)
	v_mfma_f32_16x16x32_bf16 v[36:39], v[222:225], v[52:55], v[48:51]
	s_nop 2
	s_waitcnt vmcnt(0)
	v_mfma_f32_16x16x32_bf16 v[32:35], v[226:229], v[52:55], v[32:35]
	v_lshl_add_u64 v[48:49], v[166:167], 0, v[64:65]
	v_lshl_add_u64 v[50:51], v[166:167], 0, v[66:67]
	v_lshl_add_u64 v[52:53], v[166:167], 0, v[68:69]
	v_lshl_add_u64 v[54:55], v[166:167], 0, v[70:71]
	global_load_dword v50, v[50:51], off
	s_nop 0
	global_load_dword v48, v[48:49], off
	s_nop 0
	global_load_dword v49, v[54:55], off
	global_load_dword v51, v[52:53], off
	s_nop 0
	global_load_dword v52, v[58:59], off
	global_load_dword v53, v[56:57], off
	global_load_dword v54, v[62:63], off
	global_load_dword v55, v[60:61], off
	s_waitcnt vmcnt(6)
	v_cvt_pk_bf16_f32 v48, v48, v50
	s_waitcnt vmcnt(4)
	v_cvt_pk_bf16_f32 v49, v51, v49
	s_waitcnt vmcnt(2)
	v_cvt_pk_bf16_f32 v50, v53, v52
	s_waitcnt vmcnt(0)
	v_cvt_pk_bf16_f32 v51, v55, v54
	s_waitcnt vmcnt(2)
	v_mfma_f32_16x16x32_bf16 v[160:163], v[104:107], v[48:51], 0
	s_waitcnt vmcnt(2)
	v_mfma_f32_16x16x32_bf16 v[52:55], v[116:119], v[48:51], 0
	s_waitcnt vmcnt(1)
	v_mfma_f32_16x16x32_bf16 v[56:59], v[120:123], v[48:51], 0
	s_waitcnt vmcnt(0)
	v_mfma_f32_16x16x32_bf16 v[48:51], v[132:135], v[48:51], 0
	v_lshl_add_u64 v[60:61], v[166:167], 0, v[88:89]
	v_lshl_add_u64 v[62:63], v[164:165], 0, v[86:87]
	v_cndmask_b32_e32 v61, v63, v61, vcc
	v_cndmask_b32_e32 v60, v62, v60, vcc
	v_lshl_add_u64 v[62:63], v[164:165], 0, v[90:91]
	v_lshl_add_u64 v[166:167], v[164:165], 0, v[92:93]
	v_lshl_add_u64 v[164:165], v[164:165], 0, v[102:103]
	global_load_dword v60, v[60:61], off
	s_nop 0
	global_load_dword v61, v[62:63], off
	s_nop 0
	global_load_dword v62, v[168:169], off
	global_load_dword v63, v[166:167], off
	global_load_dword v157, v[172:173], off
	global_load_dword v159, v[170:171], off
	s_nop 0
	global_load_dword v167, v[164:165], off
	global_load_dword v168, v[174:175], off
	s_waitcnt vmcnt(6)
	v_cvt_pk_bf16_f32 v164, v60, v61
	s_waitcnt vmcnt(4)
	v_cvt_pk_bf16_f32 v165, v63, v62
	s_waitcnt vmcnt(2)
	v_cvt_pk_bf16_f32 v166, v159, v157
	s_waitcnt vmcnt(0)
	v_cvt_pk_bf16_f32 v167, v168, v167
	v_mul_f32_e32 v157, v0, v0
	v_mul_f32_e32 v159, v1, v1
	s_waitcnt vmcnt(0)
	v_mfma_f32_16x16x32_bf16 v[60:63], v[230:233], v[164:167], v[52:55]
	s_nop 2
	s_waitcnt vmcnt(0)
	v_mfma_f32_16x16x32_bf16 v[56:59], v[234:237], v[164:167], v[56:59]
	s_waitcnt vmcnt(0)
	v_mfma_f32_16x16x32_bf16 v[52:55], v[238:241], v[164:167], v[160:163]
	s_nop 2
	s_waitcnt vmcnt(0)
	v_mfma_f32_16x16x32_bf16 v[48:51], v[246:249], v[164:167], v[48:51]
	v_mul_f32_e64 v160, v26, v26
	v_mul_f32_e64 v161, v27, v27
	v_pk_mul_f32 v[162:163], v[24:25], v[24:25]
	s_nop 0
	v_pk_mov_b32 v[164:165], v[162:163], v[160:161] op_sel:[1,0]
	v_mov_b32_e32 v163, v161
	v_pk_add_f32 v[160:161], v[164:165], v[162:163]
	v_pk_mul_f32 v[162:163], v[10:11], v[10:11]
	v_pk_mul_f32 v[164:165], v[8:9], v[8:9]
	v_pk_add_f32 v[160:161], v[160:161], v[160:161] op_sel:[0,1] op_sel_hi:[1,0]
	v_pk_mov_b32 v[166:167], v[164:165], v[162:163] op_sel:[1,0]
	v_mov_b32_e32 v165, v163
	v_pk_add_f32 v[162:163], v[166:167], v[164:165]
	v_mov_b32_e32 v161, v157
	v_pk_add_f32 v[162:163], v[162:163], v[162:163] op_sel:[0,1] op_sel_hi:[1,0]
	v_mul_f32_e32 v164, v2, v2
	v_mov_b32_e32 v163, v159
	v_pk_add_f32 v[160:161], v[160:161], v[162:163]
	v_mul_f32_e32 v162, v5, v5
	v_pk_fma_f32 v[162:163], v[4:5], v[4:5], v[162:163] op_sel_hi:[1,1,0]
	v_mul_f32_e32 v166, v3, v3
	v_mov_b32_e32 v163, v164
	v_mul_f32_e32 v164, v7, v7
	v_pk_fma_f32 v[164:165], v[6:7], v[6:7], v[164:165] op_sel_hi:[1,1,0]
	v_mul_f32_e32 v157, v16, v16
	v_mov_b32_e32 v165, v166
	v_pk_add_f32 v[162:163], v[162:163], v[164:165]
	v_pk_mul_f32 v[164:165], v[28:29], v[28:29]
	v_pk_add_f32 v[160:161], v[160:161], v[162:163]
	v_pk_mul_f32 v[162:163], v[30:31], v[30:31]
	v_mul_f32_e32 v159, v17, v17
	v_pk_mov_b32 v[166:167], v[164:165], v[162:163] op_sel:[1,0]
	v_mov_b32_e32 v165, v163
	v_pk_add_f32 v[162:163], v[166:167], v[164:165]
	v_pk_add_f32 v[160:161], v[160:161], v[160:161] op_sel:[0,1] op_sel_hi:[1,0]
	v_pk_add_f32 v[162:163], v[162:163], v[162:163] op_sel:[0,1] op_sel_hi:[1,0]
	v_mov_b32_e32 v161, v157
	v_mov_b32_e32 v163, v159
	v_pk_add_f32 v[160:161], v[160:161], v[162:163]
	v_mul_f32_e32 v162, v21, v21
	v_mul_f32_e32 v164, v18, v18
	v_pk_fma_f32 v[162:163], v[20:21], v[20:21], v[162:163] op_sel_hi:[1,1,0]
	v_mul_f32_e32 v166, v19, v19
	v_mov_b32_e32 v163, v164
	v_mul_f32_e32 v164, v23, v23
	v_pk_fma_f32 v[164:165], v[22:23], v[22:23], v[164:165] op_sel_hi:[1,1,0]
	v_mul_f32_e32 v157, v40, v40
	v_mov_b32_e32 v165, v166
	v_pk_add_f32 v[162:163], v[162:163], v[164:165]
	v_pk_mul_f32 v[164:165], v[12:13], v[12:13]
	v_pk_add_f32 v[160:161], v[160:161], v[162:163]
	v_pk_mul_f32 v[162:163], v[14:15], v[14:15]
	v_mul_f32_e32 v159, v41, v41
	v_pk_mov_b32 v[166:167], v[164:165], v[162:163] op_sel:[1,0]
	v_mov_b32_e32 v165, v163
	v_pk_add_f32 v[162:163], v[166:167], v[164:165]
	v_pk_add_f32 v[160:161], v[160:161], v[160:161] op_sel:[0,1] op_sel_hi:[1,0]
	v_pk_add_f32 v[162:163], v[162:163], v[162:163] op_sel:[0,1] op_sel_hi:[1,0]
	v_mov_b32_e32 v161, v157
	v_mov_b32_e32 v163, v159
	v_pk_add_f32 v[160:161], v[160:161], v[162:163]
	v_mul_f32_e32 v162, v45, v45
	v_mul_f32_e32 v164, v42, v42
	v_pk_fma_f32 v[162:163], v[44:45], v[44:45], v[162:163] op_sel_hi:[1,1,0]
	v_mul_f32_e32 v166, v43, v43
	v_mov_b32_e32 v163, v164
	v_mul_f32_e32 v164, v47, v47
	v_pk_fma_f32 v[164:165], v[46:47], v[46:47], v[164:165] op_sel_hi:[1,1,0]
	v_mul_f32_e32 v157, v60, v60
	v_mov_b32_e32 v165, v166
	v_pk_add_f32 v[162:163], v[162:163], v[164:165]
	v_pk_mul_f32 v[164:165], v[36:37], v[36:37]
	v_pk_add_f32 v[160:161], v[160:161], v[162:163]
	v_pk_mul_f32 v[162:163], v[38:39], v[38:39]
	v_mul_f32_e32 v159, v61, v61
	v_pk_mov_b32 v[166:167], v[164:165], v[162:163] op_sel:[1,0]
	v_mov_b32_e32 v165, v163
	v_pk_add_f32 v[162:163], v[166:167], v[164:165]
	v_pk_add_f32 v[160:161], v[160:161], v[160:161] op_sel:[0,1] op_sel_hi:[1,0]
	v_pk_add_f32 v[162:163], v[162:163], v[162:163] op_sel:[0,1] op_sel_hi:[1,0]
	v_mov_b32_e32 v161, v157
	v_mov_b32_e32 v163, v159
	v_pk_add_f32 v[160:161], v[160:161], v[162:163]
	v_mul_f32_e32 v162, v33, v33
	v_mul_f32_e32 v164, v62, v62
	v_pk_fma_f32 v[162:163], v[32:33], v[32:33], v[162:163] op_sel_hi:[1,1,0]
	v_mul_f32_e32 v166, v63, v63
	v_mov_b32_e32 v163, v164
	v_mul_f32_e32 v164, v35, v35
	v_pk_fma_f32 v[164:165], v[34:35], v[34:35], v[164:165] op_sel_hi:[1,1,0]
	v_mul_f32_e32 v157, v48, v48
	v_mov_b32_e32 v165, v166
	v_pk_add_f32 v[162:163], v[162:163], v[164:165]
	v_pk_mul_f32 v[164:165], v[56:57], v[56:57]
	v_pk_add_f32 v[160:161], v[160:161], v[162:163]
	v_pk_mul_f32 v[162:163], v[58:59], v[58:59]
	v_mul_f32_e32 v159, v49, v49
	v_pk_mov_b32 v[166:167], v[164:165], v[162:163] op_sel:[1,0]
	v_mov_b32_e32 v165, v163
	v_pk_add_f32 v[162:163], v[166:167], v[164:165]
	v_pk_add_f32 v[160:161], v[160:161], v[160:161] op_sel:[0,1] op_sel_hi:[1,0]
	v_pk_add_f32 v[162:163], v[162:163], v[162:163] op_sel:[0,1] op_sel_hi:[1,0]
	v_mov_b32_e32 v161, v157
	v_mov_b32_e32 v163, v159
	v_pk_add_f32 v[160:161], v[160:161], v[162:163]
	v_mul_f32_e32 v162, v53, v53
	v_mul_f32_e32 v164, v50, v50
	v_pk_fma_f32 v[162:163], v[52:53], v[52:53], v[162:163] op_sel_hi:[1,1,0]
	v_mul_f32_e32 v166, v51, v51
	v_mov_b32_e32 v163, v164
	v_mul_f32_e32 v164, v55, v55
	v_pk_fma_f32 v[164:165], v[54:55], v[54:55], v[164:165] op_sel_hi:[1,1,0]
	v_xor_b32_e32 v159, 16, v245
	v_mov_b32_e32 v165, v166
	v_pk_add_f32 v[162:163], v[162:163], v[164:165]
	s_nop 0
	v_pk_add_f32 v[160:161], v[160:161], v[162:163]
	s_nop 0
	v_add_f32_e32 v157, v160, v161
	v_and_b32_e32 v160, 64, v245
	v_add_u32_e32 v160, 64, v160
	v_cmp_lt_i32_e64 s[36:37], v159, v160
	s_nop 1
	v_cndmask_b32_e64 v159, v245, v159, s[36:37]
	v_lshlrev_b32_e32 v159, 2, v159
	ds_bpermute_b32 v159, v159, v157
	s_waitcnt lgkmcnt(0)
	v_add_f32_e32 v157, v157, v159
	v_xor_b32_e32 v159, 32, v245
	v_cmp_lt_i32_e64 s[36:37], v159, v160
	v_add_u32_e32 v160, s3, v158
	v_ashrrev_i32_e32 v161, 31, v160
	v_cndmask_b32_e64 v159, v245, v159, s[36:37]
	v_lshlrev_b32_e32 v159, 2, v159
	ds_bpermute_b32 v159, v159, v157
	v_lshlrev_b64 v[160:161], 11, v[160:161]
	v_lshl_add_u64 v[160:161], s[84:85], 0, v[160:161]
	s_add_i32 s3, s3, s9
	s_cmpk_lt_i32 s0, 0x1000
	s_waitcnt lgkmcnt(0)
	v_add_f32_e32 v157, v157, v159
	v_fmamk_f32 v157, v157, 0x3b800000, v244
	v_cmp_gt_f32_e64 s[36:37], s7, v157
	v_mul_f32_e32 v159, 0x4b800000, v157
	s_nop 0
	v_cndmask_b32_e64 v157, v157, v159, s[36:37]
	v_rsq_f32_e32 v157, v157
	s_nop 0
	v_mul_f32_e32 v159, 0x45800000, v157
	v_cndmask_b32_e64 v159, v157, v159, s[36:37]
	v_mov_b32_e32 v157, v209
	v_lshl_add_u64 v[160:161], v[160:161], 0, v[156:157]
	v_lshl_add_u64 v[162:163], v[160:161], 0, s[18:19]
	v_mbcnt_lo_u32_b32 v154, -1, 0
	v_mbcnt_hi_u32_b32 v154, -1, v154
	v_lshrrev_b32_e32 v154, 4, v154
	v_and_b32_e32 v154, 1, v154
	v_mul_u32_u24_e32 v154, 24, v154
	v_mov_b32_e32 v155, v209
	v_lshl_add_u64 v[152:153], v[162:163], 0, v[154:155]
	v_mul_f32_e32 v24, v24, v159
	v_mul_f32_e32 v25, v25, v159
	v_cvt_pk_bf16_f32 v136, v24, v25
	v_mul_f32_e32 v26, v26, v159
	v_mul_f32_e32 v27, v27, v159
	v_cvt_pk_bf16_f32 v137, v26, v27
	v_mul_f32_e32 v8, v8, v159
	v_mul_f32_e32 v9, v9, v159
	v_cvt_pk_bf16_f32 v138, v8, v9
	v_mul_f32_e32 v10, v10, v159
	v_mul_f32_e32 v11, v11, v159
	v_cvt_pk_bf16_f32 v139, v10, v11
	s_nop 1
	v_permlane16_swap_b32_e32 v136, v138
	v_permlane16_swap_b32_e32 v137, v139
	global_store_dwordx4 v[152:153], v[136:139], off
	v_mul_f32_e32 v4, v4, v159
	v_mul_f32_e32 v5, v5, v159
	v_cvt_pk_bf16_f32 v148, v4, v5
	v_mul_f32_e32 v6, v6, v159
	v_mul_f32_e32 v7, v7, v159
	v_cvt_pk_bf16_f32 v149, v6, v7
	v_mul_f32_e32 v0, v0, v159
	v_mul_f32_e32 v1, v1, v159
	v_cvt_pk_bf16_f32 v150, v0, v1
	v_mul_f32_e32 v2, v2, v159
	v_mul_f32_e32 v3, v3, v159
	v_cvt_pk_bf16_f32 v151, v2, v3
	s_nop 1
	v_permlane16_swap_b32_e32 v148, v150
	v_permlane16_swap_b32_e32 v149, v151
	global_store_dwordx4 v[152:153], v[148:151], off offset:64
	v_mul_f32_e32 v28, v28, v159
	v_mul_f32_e32 v29, v29, v159
	v_cvt_pk_bf16_f32 v136, v28, v29
	v_mul_f32_e32 v30, v30, v159
	v_mul_f32_e32 v31, v31, v159
	v_cvt_pk_bf16_f32 v137, v30, v31
	v_mul_f32_e32 v20, v20, v159
	v_mul_f32_e32 v21, v21, v159
	v_cvt_pk_bf16_f32 v138, v20, v21
	v_mul_f32_e32 v22, v22, v159
	v_mul_f32_e32 v23, v23, v159
	v_cvt_pk_bf16_f32 v139, v22, v23
	s_nop 1
	v_permlane16_swap_b32_e32 v136, v138
	v_permlane16_swap_b32_e32 v137, v139
	global_store_dwordx4 v[152:153], v[136:139], off offset:128
	v_mul_f32_e32 v16, v16, v159
	v_mul_f32_e32 v17, v17, v159
	v_cvt_pk_bf16_f32 v148, v16, v17
	v_mul_f32_e32 v18, v18, v159
	v_mul_f32_e32 v19, v19, v159
	v_cvt_pk_bf16_f32 v149, v18, v19
	v_mul_f32_e32 v12, v12, v159
	v_mul_f32_e32 v13, v13, v159
	v_cvt_pk_bf16_f32 v150, v12, v13
	v_mul_f32_e32 v14, v14, v159
	v_mul_f32_e32 v15, v15, v159
	v_cvt_pk_bf16_f32 v151, v14, v15
	s_nop 1
	v_permlane16_swap_b32_e32 v148, v150
	v_permlane16_swap_b32_e32 v149, v151
	global_store_dwordx4 v[152:153], v[148:151], off offset:192
	v_mul_f32_e32 v44, v44, v159
	v_mul_f32_e32 v45, v45, v159
	v_cvt_pk_bf16_f32 v136, v44, v45
	v_mul_f32_e32 v46, v46, v159
	v_mul_f32_e32 v47, v47, v159
	v_cvt_pk_bf16_f32 v137, v46, v47
	v_mul_f32_e32 v40, v40, v159
	v_mul_f32_e32 v41, v41, v159
	v_cvt_pk_bf16_f32 v138, v40, v41
	v_mul_f32_e32 v42, v42, v159
	v_mul_f32_e32 v43, v43, v159
	v_cvt_pk_bf16_f32 v139, v42, v43
	s_nop 1
	v_permlane16_swap_b32_e32 v136, v138
	v_permlane16_swap_b32_e32 v137, v139
	global_store_dwordx4 v[152:153], v[136:139], off offset:256
	v_mul_f32_e32 v36, v36, v159
	v_mul_f32_e32 v37, v37, v159
	v_cvt_pk_bf16_f32 v148, v36, v37
	v_mul_f32_e32 v38, v38, v159
	v_mul_f32_e32 v39, v39, v159
	v_cvt_pk_bf16_f32 v149, v38, v39
	v_mul_f32_e32 v32, v32, v159
	v_mul_f32_e32 v33, v33, v159
	v_cvt_pk_bf16_f32 v150, v32, v33
	v_mul_f32_e32 v34, v34, v159
	v_mul_f32_e32 v35, v35, v159
	v_cvt_pk_bf16_f32 v151, v34, v35
	s_nop 1
	v_permlane16_swap_b32_e32 v148, v150
	v_permlane16_swap_b32_e32 v149, v151
	global_store_dwordx4 v[152:153], v[148:151], off offset:320
	v_mul_f32_e32 v60, v60, v159
	v_mul_f32_e32 v61, v61, v159
	v_cvt_pk_bf16_f32 v136, v60, v61
	v_mul_f32_e32 v62, v62, v159
	v_mul_f32_e32 v63, v63, v159
	v_cvt_pk_bf16_f32 v137, v62, v63
	v_mul_f32_e32 v56, v56, v159
	v_mul_f32_e32 v57, v57, v159
	v_cvt_pk_bf16_f32 v138, v56, v57
	v_mul_f32_e32 v58, v58, v159
	v_mul_f32_e32 v59, v59, v159
	v_cvt_pk_bf16_f32 v139, v58, v59
	s_nop 1
	v_permlane16_swap_b32_e32 v136, v138
	v_permlane16_swap_b32_e32 v137, v139
	global_store_dwordx4 v[152:153], v[136:139], off offset:384
	v_mul_f32_e32 v52, v52, v159
	v_mul_f32_e32 v53, v53, v159
	v_cvt_pk_bf16_f32 v148, v52, v53
	v_mul_f32_e32 v54, v54, v159
	v_mul_f32_e32 v55, v55, v159
	v_cvt_pk_bf16_f32 v149, v54, v55
	v_mul_f32_e32 v48, v48, v159
	v_mul_f32_e32 v49, v49, v159
	v_cvt_pk_bf16_f32 v150, v48, v49
	v_mul_f32_e32 v50, v50, v159
	v_mul_f32_e32 v51, v51, v159
	v_cvt_pk_bf16_f32 v151, v50, v51
	s_nop 1
	v_permlane16_swap_b32_e32 v148, v150
	v_permlane16_swap_b32_e32 v149, v151
	global_store_dwordx4 v[152:153], v[148:151], off offset:448
	s_cbranch_scc1 .LBB0_362
